# scan consumer: pair-shared b64 LDS reads with DPP quad broadcast and permlane16 cross-row reduce
# speedup vs baseline: 1.0069x; 1.0038x over previous
; __device__ __forceinline__ float allreduce16(float x) { x += dppf(x, 0); x += dppf(x, 1); x += dppf(x, 2); x += dppf(x, 3); return x; }
; __device__ void rw_scan(const Params& p, int l, unsigned char* shm, int item) {
;     ...
;         __builtin_amdgcn_s_setprio(3);
;         const int rowl = w * 4 + (lane >> 4), ks = (lane & 15) * 4;
;         f32x2 S01 = (f32x2){0.f, 0.f}, S23 = (f32x2){0.f, 0.f};
;         float* pp = part + w * 1024 + (lane >> 4) * 16 + (lane & 15);
;         __syncthreads();
;         for (int ck = 0; ck < T / TC; ++ck) {
;             const float* sr = (const float*)(shm + (ck & 1) * RWB) + ks; const float* sv = (const float*)(shm + (ck & 1) * RWB) + 5 * 2048 + rowl;
;             f32x4 a4 = *(const f32x4*)(sr + 3 * 2048), w4 = *(const f32x4*)(sr + 2048), b4 = *(const f32x4*)(sr + 4 * 2048), k4 = *(const f32x4*)(sr + 2 * 2048), r4 = *(const f32x4*)sr;
;             float vv = sv[0];
; #pragma unroll
;             for (int hs = 0; hs < 2; ++hs) {
; #pragma unroll
;                 for (int s2 = 0; s2 < 16; ++s2) {
;                     const int s = hs * 16 + s2, sn = (s + 1) & (TC - 1);
;                     const f32x4 na4 = *(const f32x4*)(sr + 3 * 2048 + sn * 64), nw4 = *(const f32x4*)(sr + 2048 + sn * 64), nb4 = *(const f32x4*)(sr + 4 * 2048 + sn * 64), nk4 = *(const f32x4*)(sr + 2 * 2048 + sn * 64), nr4 = *(const f32x4*)(sr + sn * 64);
;                     const float nvv = sv[sn * 16];
;                     f32x2 tq = S01 * (f32x2){a4[0], a4[1]}; tq = S23 * (f32x2){a4[2], a4[3]} + tq;
;                     const float sav = allreduce16(tq[0] + tq[1]);
;                     f32x2 u0 = (f32x2){b4[0], b4[1]} * sav, u1 = (f32x2){b4[2], b4[3]} * sav;
;                     u0 = (f32x2){k4[0], k4[1]} * vv + u0; u1 = (f32x2){k4[2], k4[3]} * vv + u1;
;                     S01 = S01 * (f32x2){w4[0], w4[1]} + u0; S23 = S23 * (f32x2){w4[2], w4[3]} + u1;
;                     f32x2 oq = S01 * (f32x2){r4[0], r4[1]}; oq = S23 * (f32x2){r4[2], r4[3]} + oq;
;                     pp[s2 * 64] = oq[0] + oq[1];
;                     a4 = na4; w4 = nw4; b4 = nb4; k4 = nk4; r4 = nr4; vv = nvv;
;                 }
.LBB0_302:
	s_or_b64 exec, exec, s[0:1]
	s_mul_hi_i32 s0, s10, 0x2aaaaaab
	s_lshr_b32 s1, s0, 31
	s_ashr_i32 s2, s0, 4
	s_and_b32 s12, s10, 3
	s_add_i32 s2, s2, s1
	s_cmp_eq_u32 s9, 0
	v_ashrrev_i32_e32 v4, 6, v3
	s_cselect_b64 vcc, -1, 0
	v_and_b32_e32 v74, 63, v3
	v_cmp_gt_i32_e64 s[0:1], 4, v4
	v_and_b32_e32 v5, 48, v3
	s_waitcnt lgkmcnt(0)
	s_barrier
	s_and_saveexec_b64 s[4:5], s[0:1]
	s_xor_b64 s[0:1], exec, s[4:5]
	s_cbranch_execz .LBB0_306
	s_and_b64 s[4:5], vcc, exec
	s_mov_b32 s3, 0x6504000
	s_cselect_b32 s4, s3, 0x2b504000
	s_add_u32 s5, s94, s4
	s_mov_b32 s3, 0
	s_addc_u32 s10, s95, 0
	s_setprio 3
	s_lshl_b32 s6, s8, 6
	v_readlane_b32 s4, v253, 45
	s_ashr_i32 s7, s6, 31
	s_lshl_b64 s[6:7], s[6:7], 2
	v_lshl_add_u32 v0, v4, 12, s4
	s_lshl_b32 s4, s2, 14
	s_add_u32 s5, s5, s6
	s_addc_u32 s7, s10, s7
	s_lshl_b32 s6, s12, 6
	v_lshlrev_b32_e32 v22, 2, v4
	v_lshlrev_b32_e32 v4, 2, v5
	v_lshlrev_b32_e32 v5, 2, v2
	s_add_u32 s6, s5, s6
	v_add3_u32 v30, v0, v4, v5
	v_lshrrev_b32_e32 v32, 2, v74
	v_and_b32_e32 v4, 3, v3
	v_ashrrev_i32_e32 v23, 31, v22
	s_addc_u32 s7, s7, 0
	v_lshlrev_b32_e32 v31, 4, v2
	v_lshl_add_u32 v5, v32, 8, v0
	v_lshl_add_u64 v[2:3], v[22:23], 2, s[6:7]
	v_lshlrev_b32_e32 v0, 2, v4
	v_lshrrev_b32_e32 v6, 4, v74
	v_lshlrev_b32_e32 v7, 6, v4
	v_lshl_add_u64 v[24:25], v[2:3], 0, v[0:1]
	v_mov_b32_e32 v2, 0
	v_xor_b32_e32 v23, 0x3fef, v32
	v_lshlrev_b32_e32 v33, 2, v6
	v_add_u32_e32 v34, v5, v7
	v_mov_b32_e32 v3, v2
	v_mov_b32_e32 v4, v2
	v_mov_b32_e32 v5, v2
	s_movk_i32 s10, 0xc00
	v_lshrrev_b32_e32 v6, 4, v74
	v_and_b32_e32 v7, 1, v74
	v_bfe_u32 v8, v74, 1, 3
	v_and_b32_e32 v9, 1, v6
	v_lshl_add_u32 v8, v9, 3, v8
	v_lshrrev_b32_e32 v6, 1, v6
	v_lshl_add_u32 v6, v6, 1, v7
	v_lshlrev_b32_e32 v31, 4, v8
	v_lshl_add_u32 v31, v7, 3, v31
	v_lshlrev_b32_e32 v33, 2, v6
	v_lshlrev_b32_e32 v30, 10, v22
	v_add_u32_e32 v30, 0x15000, v30
	v_lshl_add_u32 v30, v6, 6, v30
	v_lshl_add_u32 v30, v8, 2, v30
	s_barrier
.LBB0_304:
	s_bitcmp1_b32 s3, 0
	s_cselect_b32 s5, 0xa800, 0
	v_add_u32_e32 v35, s5, v31
	v_lshlrev_b32_e32 v0, 2, v22
	v_add3_u32 v36, s5, v0, v33
	v_add_u32_e32 v37, 0xa000, v36
	v_add_u32_e32 v38, 0xa400, v36
	ds_read_b64 v[40:41], v35 offset:24576
	ds_read_b64 v[48:49], v35 offset:8192
	ds_read_b64 v[56:57], v35 offset:32768
	ds_read_b64 v[64:65], v35 offset:16384
	ds_read_b64 v[72:73], v35 offset:0
	ds_read2_b32 v[120:121], v37 offset0:0 offset1:16
	ds_read_b64 v[42:43], v35 offset:24832
	ds_read_b64 v[50:51], v35 offset:8448
	ds_read_b64 v[58:59], v35 offset:33024
	ds_read_b64 v[66:67], v35 offset:16640
	ds_read_b64 v[74:75], v35 offset:256
	s_waitcnt lgkmcnt(5)
	v_mul_f32_dpp v10, v40, v2 quad_perm:[0,0,2,2] row_mask:0xf bank_mask:0xf bound_ctrl:1
	v_mul_f32_dpp v6, v64, v120 quad_perm:[0,0,2,2] row_mask:0xf bank_mask:0xf bound_ctrl:1
	v_fmac_f32_dpp v10, v41, v3 quad_perm:[0,0,2,2] row_mask:0xf bank_mask:0xf bound_ctrl:1
	v_mul_f32_dpp v7, v65, v120 quad_perm:[0,0,2,2] row_mask:0xf bank_mask:0xf bound_ctrl:1
	v_fmac_f32_dpp v10, v40, v4 quad_perm:[1,1,3,3] row_mask:0xf bank_mask:0xf bound_ctrl:1
	v_mul_f32_dpp v8, v64, v120 quad_perm:[1,1,3,3] row_mask:0xf bank_mask:0xf bound_ctrl:1
	v_fmac_f32_dpp v10, v41, v5 quad_perm:[1,1,3,3] row_mask:0xf bank_mask:0xf bound_ctrl:1
	v_mul_f32_dpp v9, v65, v120 quad_perm:[1,1,3,3] row_mask:0xf bank_mask:0xf bound_ctrl:1
	v_fmac_f32_dpp v6, v48, v2 quad_perm:[0,0,2,2] row_mask:0xf bank_mask:0xf bound_ctrl:1
	v_add_f32_dpp v10, v10, v10 quad_perm:[2,3,0,1] row_mask:0xf bank_mask:0xf bound_ctrl:1
	v_fmac_f32_dpp v7, v49, v3 quad_perm:[0,0,2,2] row_mask:0xf bank_mask:0xf bound_ctrl:1
	v_fmac_f32_dpp v8, v48, v4 quad_perm:[1,1,3,3] row_mask:0xf bank_mask:0xf bound_ctrl:1
	v_add_f32_dpp v10, v10, v10 row_ror:4 row_mask:0xf bank_mask:0xf bound_ctrl:1
	v_fmac_f32_dpp v9, v49, v5 quad_perm:[1,1,3,3] row_mask:0xf bank_mask:0xf bound_ctrl:1
	s_nop 0
	v_add_f32_dpp v10, v10, v10 row_ror:8 row_mask:0xf bank_mask:0xf bound_ctrl:1
	v_mov_b32_e32 v14, v10
	s_nop 0
	s_nop 0
	v_permlane16_swap_b32 v10, v14
	v_add_f32_e32 v10, v10, v14
	v_fmac_f32_dpp v6, v56, v10 quad_perm:[0,0,2,2] row_mask:0xf bank_mask:0xf bound_ctrl:1
	v_fmac_f32_dpp v7, v57, v10 quad_perm:[0,0,2,2] row_mask:0xf bank_mask:0xf bound_ctrl:1
	v_fmac_f32_dpp v8, v56, v10 quad_perm:[1,1,3,3] row_mask:0xf bank_mask:0xf bound_ctrl:1
	v_fmac_f32_dpp v9, v57, v10 quad_perm:[1,1,3,3] row_mask:0xf bank_mask:0xf bound_ctrl:1
	ds_read_b64 v[44:45], v35 offset:25088
	ds_read_b64 v[52:53], v35 offset:8704
	ds_read_b64 v[60:61], v35 offset:33280
	ds_read_b64 v[68:69], v35 offset:16896
	ds_read_b64 v[76:77], v35 offset:512
	ds_read2_b32 v[122:123], v37 offset0:32 offset1:48
	s_waitcnt lgkmcnt(6)
; __device__ __forceinline__ float allreduce16(float x) { x += dppf(x, 0); x += dppf(x, 1); x += dppf(x, 2); x += dppf(x, 3); return x; }
; __device__ void rw_scan(const Params& p, int l, unsigned char* shm, int item) {
;     ...
;                 for (int s2 = 0; s2 < 16; ++s2) {
;                     const int s = hs * 16 + s2, sn = (s + 1) & (TC - 1);
;                     const f32x4 na4 = *(const f32x4*)(sr + 3 * 2048 + sn * 64), nw4 = *(const f32x4*)(sr + 2048 + sn * 64), nb4 = *(const f32x4*)(sr + 4 * 2048 + sn * 64), nk4 = *(const f32x4*)(sr + 2 * 2048 + sn * 64), nr4 = *(const f32x4*)(sr + sn * 64);
;                     const float nvv = sv[sn * 16];
;                     f32x2 tq = S01 * (f32x2){a4[0], a4[1]}; tq = S23 * (f32x2){a4[2], a4[3]} + tq;
;                     const float sav = allreduce16(tq[0] + tq[1]);
;                     f32x2 u0 = (f32x2){b4[0], b4[1]} * sav, u1 = (f32x2){b4[2], b4[3]} * sav;
;                     u0 = (f32x2){k4[0], k4[1]} * vv + u0; u1 = (f32x2){k4[2], k4[3]} * vv + u1;
;                     S01 = S01 * (f32x2){w4[0], w4[1]} + u0; S23 = S23 * (f32x2){w4[2], w4[3]} + u1;
;                     f32x2 oq = S01 * (f32x2){r4[0], r4[1]}; oq = S23 * (f32x2){r4[2], r4[3]} + oq;
;                     pp[s2 * 64] = oq[0] + oq[1];
;                     a4 = na4; w4 = nw4; b4 = nb4; k4 = nk4; r4 = nr4; vv = nvv;
;                 }
	v_mul_f32_dpp v11, v42, v6 quad_perm:[0,0,2,2] row_mask:0xf bank_mask:0xf bound_ctrl:1
	v_mul_f32_dpp v2, v66, v121 quad_perm:[0,0,2,2] row_mask:0xf bank_mask:0xf bound_ctrl:1
	v_fmac_f32_dpp v11, v43, v7 quad_perm:[0,0,2,2] row_mask:0xf bank_mask:0xf bound_ctrl:1
	v_mul_f32_dpp v3, v67, v121 quad_perm:[0,0,2,2] row_mask:0xf bank_mask:0xf bound_ctrl:1
	v_fmac_f32_dpp v11, v42, v8 quad_perm:[1,1,3,3] row_mask:0xf bank_mask:0xf bound_ctrl:1
	v_mul_f32_dpp v4, v66, v121 quad_perm:[1,1,3,3] row_mask:0xf bank_mask:0xf bound_ctrl:1
	v_fmac_f32_dpp v11, v43, v9 quad_perm:[1,1,3,3] row_mask:0xf bank_mask:0xf bound_ctrl:1
	v_mul_f32_dpp v5, v67, v121 quad_perm:[1,1,3,3] row_mask:0xf bank_mask:0xf bound_ctrl:1
	v_fmac_f32_dpp v2, v50, v6 quad_perm:[0,0,2,2] row_mask:0xf bank_mask:0xf bound_ctrl:1
	v_add_f32_dpp v11, v11, v11 quad_perm:[2,3,0,1] row_mask:0xf bank_mask:0xf bound_ctrl:1
	v_fmac_f32_dpp v3, v51, v7 quad_perm:[0,0,2,2] row_mask:0xf bank_mask:0xf bound_ctrl:1
	v_fmac_f32_dpp v4, v50, v8 quad_perm:[1,1,3,3] row_mask:0xf bank_mask:0xf bound_ctrl:1
	v_add_f32_dpp v11, v11, v11 row_ror:4 row_mask:0xf bank_mask:0xf bound_ctrl:1
	v_fmac_f32_dpp v5, v51, v9 quad_perm:[1,1,3,3] row_mask:0xf bank_mask:0xf bound_ctrl:1
	v_mul_f32_dpp v12, v72, v6 quad_perm:[0,0,2,2] row_mask:0xf bank_mask:0xf bound_ctrl:1
	v_add_f32_dpp v11, v11, v11 row_ror:8 row_mask:0xf bank_mask:0xf bound_ctrl:1
	v_mov_b32_e32 v15, v11
	v_fmac_f32_dpp v12, v73, v7 quad_perm:[0,0,2,2] row_mask:0xf bank_mask:0xf bound_ctrl:1
	v_fmac_f32_dpp v12, v72, v8 quad_perm:[1,1,3,3] row_mask:0xf bank_mask:0xf bound_ctrl:1
	v_permlane16_swap_b32 v11, v15
	v_add_f32_e32 v11, v11, v15
	v_fmac_f32_dpp v2, v58, v11 quad_perm:[0,0,2,2] row_mask:0xf bank_mask:0xf bound_ctrl:1
	v_fmac_f32_dpp v3, v59, v11 quad_perm:[0,0,2,2] row_mask:0xf bank_mask:0xf bound_ctrl:1
	v_fmac_f32_dpp v4, v58, v11 quad_perm:[1,1,3,3] row_mask:0xf bank_mask:0xf bound_ctrl:1
	v_fmac_f32_dpp v5, v59, v11 quad_perm:[1,1,3,3] row_mask:0xf bank_mask:0xf bound_ctrl:1
	v_fmac_f32_dpp v12, v73, v9 quad_perm:[1,1,3,3] row_mask:0xf bank_mask:0xf bound_ctrl:1
	ds_read_b64 v[46:47], v35 offset:25344
	ds_read_b64 v[54:55], v35 offset:8960
	ds_read_b64 v[62:63], v35 offset:33536
	ds_read_b64 v[70:71], v35 offset:17152
	ds_read_b64 v[78:79], v35 offset:768
	s_waitcnt lgkmcnt(5)
	v_mul_f32_dpp v10, v44, v2 quad_perm:[0,0,2,2] row_mask:0xf bank_mask:0xf bound_ctrl:1
	v_mul_f32_dpp v6, v68, v122 quad_perm:[0,0,2,2] row_mask:0xf bank_mask:0xf bound_ctrl:1
	v_fmac_f32_dpp v10, v45, v3 quad_perm:[0,0,2,2] row_mask:0xf bank_mask:0xf bound_ctrl:1
	v_mul_f32_dpp v7, v69, v122 quad_perm:[0,0,2,2] row_mask:0xf bank_mask:0xf bound_ctrl:1
	v_fmac_f32_dpp v10, v44, v4 quad_perm:[1,1,3,3] row_mask:0xf bank_mask:0xf bound_ctrl:1
	v_mul_f32_dpp v8, v68, v122 quad_perm:[1,1,3,3] row_mask:0xf bank_mask:0xf bound_ctrl:1
	v_fmac_f32_dpp v10, v45, v5 quad_perm:[1,1,3,3] row_mask:0xf bank_mask:0xf bound_ctrl:1
	v_mul_f32_dpp v9, v69, v122 quad_perm:[1,1,3,3] row_mask:0xf bank_mask:0xf bound_ctrl:1
	v_fmac_f32_dpp v6, v52, v2 quad_perm:[0,0,2,2] row_mask:0xf bank_mask:0xf bound_ctrl:1
	v_add_f32_dpp v10, v10, v10 quad_perm:[2,3,0,1] row_mask:0xf bank_mask:0xf bound_ctrl:1
	v_fmac_f32_dpp v7, v53, v3 quad_perm:[0,0,2,2] row_mask:0xf bank_mask:0xf bound_ctrl:1
	v_fmac_f32_dpp v8, v52, v4 quad_perm:[1,1,3,3] row_mask:0xf bank_mask:0xf bound_ctrl:1
	v_add_f32_dpp v10, v10, v10 row_ror:4 row_mask:0xf bank_mask:0xf bound_ctrl:1
	v_fmac_f32_dpp v9, v53, v5 quad_perm:[1,1,3,3] row_mask:0xf bank_mask:0xf bound_ctrl:1
	v_mul_f32_dpp v13, v74, v2 quad_perm:[0,0,2,2] row_mask:0xf bank_mask:0xf bound_ctrl:1
	v_add_f32_dpp v10, v10, v10 row_ror:8 row_mask:0xf bank_mask:0xf bound_ctrl:1
	v_mov_b32_e32 v14, v10
	v_fmac_f32_dpp v13, v75, v3 quad_perm:[0,0,2,2] row_mask:0xf bank_mask:0xf bound_ctrl:1
	v_fmac_f32_dpp v13, v74, v4 quad_perm:[1,1,3,3] row_mask:0xf bank_mask:0xf bound_ctrl:1
	v_permlane16_swap_b32 v10, v14
	v_add_f32_e32 v10, v10, v14
	v_fmac_f32_dpp v6, v60, v10 quad_perm:[0,0,2,2] row_mask:0xf bank_mask:0xf bound_ctrl:1
	v_fmac_f32_dpp v7, v61, v10 quad_perm:[0,0,2,2] row_mask:0xf bank_mask:0xf bound_ctrl:1
	v_fmac_f32_dpp v8, v60, v10 quad_perm:[1,1,3,3] row_mask:0xf bank_mask:0xf bound_ctrl:1
	v_fmac_f32_dpp v9, v61, v10 quad_perm:[1,1,3,3] row_mask:0xf bank_mask:0xf bound_ctrl:1
	v_fmac_f32_dpp v13, v75, v5 quad_perm:[1,1,3,3] row_mask:0xf bank_mask:0xf bound_ctrl:1
	ds_write2st64_b32 v30, v12, v13 offset0:0 offset1:1
	ds_read_b64 v[40:41], v35 offset:25600
	ds_read_b64 v[48:49], v35 offset:9216
	ds_read_b64 v[56:57], v35 offset:33792
	ds_read_b64 v[64:65], v35 offset:17408
	ds_read_b64 v[72:73], v35 offset:1024
	ds_read2_b32 v[124:125], v37 offset0:64 offset1:80
	s_waitcnt lgkmcnt(7)
; __device__ __forceinline__ float allreduce16(float x) { x += dppf(x, 0); x += dppf(x, 1); x += dppf(x, 2); x += dppf(x, 3); return x; }
; __device__ void rw_scan(const Params& p, int l, unsigned char* shm, int item) {
;     ...
;                 for (int s2 = 0; s2 < 16; ++s2) {
;                     const int s = hs * 16 + s2, sn = (s + 1) & (TC - 1);
;                     const f32x4 na4 = *(const f32x4*)(sr + 3 * 2048 + sn * 64), nw4 = *(const f32x4*)(sr + 2048 + sn * 64), nb4 = *(const f32x4*)(sr + 4 * 2048 + sn * 64), nk4 = *(const f32x4*)(sr + 2 * 2048 + sn * 64), nr4 = *(const f32x4*)(sr + sn * 64);
;                     const float nvv = sv[sn * 16];
;                     f32x2 tq = S01 * (f32x2){a4[0], a4[1]}; tq = S23 * (f32x2){a4[2], a4[3]} + tq;
;                     const float sav = allreduce16(tq[0] + tq[1]);
;                     f32x2 u0 = (f32x2){b4[0], b4[1]} * sav, u1 = (f32x2){b4[2], b4[3]} * sav;
;                     u0 = (f32x2){k4[0], k4[1]} * vv + u0; u1 = (f32x2){k4[2], k4[3]} * vv + u1;
;                     S01 = S01 * (f32x2){w4[0], w4[1]} + u0; S23 = S23 * (f32x2){w4[2], w4[3]} + u1;
;                     f32x2 oq = S01 * (f32x2){r4[0], r4[1]}; oq = S23 * (f32x2){r4[2], r4[3]} + oq;
;                     pp[s2 * 64] = oq[0] + oq[1];
;                     a4 = na4; w4 = nw4; b4 = nb4; k4 = nk4; r4 = nr4; vv = nvv;
;                 }
	v_mul_f32_dpp v11, v46, v6 quad_perm:[0,0,2,2] row_mask:0xf bank_mask:0xf bound_ctrl:1
	v_mul_f32_dpp v2, v70, v123 quad_perm:[0,0,2,2] row_mask:0xf bank_mask:0xf bound_ctrl:1
	v_fmac_f32_dpp v11, v47, v7 quad_perm:[0,0,2,2] row_mask:0xf bank_mask:0xf bound_ctrl:1
	v_mul_f32_dpp v3, v71, v123 quad_perm:[0,0,2,2] row_mask:0xf bank_mask:0xf bound_ctrl:1
	v_fmac_f32_dpp v11, v46, v8 quad_perm:[1,1,3,3] row_mask:0xf bank_mask:0xf bound_ctrl:1
	v_mul_f32_dpp v4, v70, v123 quad_perm:[1,1,3,3] row_mask:0xf bank_mask:0xf bound_ctrl:1
	v_fmac_f32_dpp v11, v47, v9 quad_perm:[1,1,3,3] row_mask:0xf bank_mask:0xf bound_ctrl:1
	v_mul_f32_dpp v5, v71, v123 quad_perm:[1,1,3,3] row_mask:0xf bank_mask:0xf bound_ctrl:1
	v_fmac_f32_dpp v2, v54, v6 quad_perm:[0,0,2,2] row_mask:0xf bank_mask:0xf bound_ctrl:1
	v_add_f32_dpp v11, v11, v11 quad_perm:[2,3,0,1] row_mask:0xf bank_mask:0xf bound_ctrl:1
	v_fmac_f32_dpp v3, v55, v7 quad_perm:[0,0,2,2] row_mask:0xf bank_mask:0xf bound_ctrl:1
	v_fmac_f32_dpp v4, v54, v8 quad_perm:[1,1,3,3] row_mask:0xf bank_mask:0xf bound_ctrl:1
	v_add_f32_dpp v11, v11, v11 row_ror:4 row_mask:0xf bank_mask:0xf bound_ctrl:1
	v_fmac_f32_dpp v5, v55, v9 quad_perm:[1,1,3,3] row_mask:0xf bank_mask:0xf bound_ctrl:1
	v_mul_f32_dpp v12, v76, v6 quad_perm:[0,0,2,2] row_mask:0xf bank_mask:0xf bound_ctrl:1
	v_add_f32_dpp v11, v11, v11 row_ror:8 row_mask:0xf bank_mask:0xf bound_ctrl:1
	v_mov_b32_e32 v15, v11
	v_fmac_f32_dpp v12, v77, v7 quad_perm:[0,0,2,2] row_mask:0xf bank_mask:0xf bound_ctrl:1
	v_fmac_f32_dpp v12, v76, v8 quad_perm:[1,1,3,3] row_mask:0xf bank_mask:0xf bound_ctrl:1
	v_permlane16_swap_b32 v11, v15
	v_add_f32_e32 v11, v11, v15
	v_fmac_f32_dpp v2, v62, v11 quad_perm:[0,0,2,2] row_mask:0xf bank_mask:0xf bound_ctrl:1
	v_fmac_f32_dpp v3, v63, v11 quad_perm:[0,0,2,2] row_mask:0xf bank_mask:0xf bound_ctrl:1
	v_fmac_f32_dpp v4, v62, v11 quad_perm:[1,1,3,3] row_mask:0xf bank_mask:0xf bound_ctrl:1
	v_fmac_f32_dpp v5, v63, v11 quad_perm:[1,1,3,3] row_mask:0xf bank_mask:0xf bound_ctrl:1
	v_fmac_f32_dpp v12, v77, v9 quad_perm:[1,1,3,3] row_mask:0xf bank_mask:0xf bound_ctrl:1
	ds_read_b64 v[42:43], v35 offset:25856
	ds_read_b64 v[50:51], v35 offset:9472
	ds_read_b64 v[58:59], v35 offset:34048
	ds_read_b64 v[66:67], v35 offset:17664
	ds_read_b64 v[74:75], v35 offset:1280
	s_waitcnt lgkmcnt(5)
	v_mul_f32_dpp v10, v40, v2 quad_perm:[0,0,2,2] row_mask:0xf bank_mask:0xf bound_ctrl:1
	v_mul_f32_dpp v6, v64, v124 quad_perm:[0,0,2,2] row_mask:0xf bank_mask:0xf bound_ctrl:1
	v_fmac_f32_dpp v10, v41, v3 quad_perm:[0,0,2,2] row_mask:0xf bank_mask:0xf bound_ctrl:1
	v_mul_f32_dpp v7, v65, v124 quad_perm:[0,0,2,2] row_mask:0xf bank_mask:0xf bound_ctrl:1
	v_fmac_f32_dpp v10, v40, v4 quad_perm:[1,1,3,3] row_mask:0xf bank_mask:0xf bound_ctrl:1
	v_mul_f32_dpp v8, v64, v124 quad_perm:[1,1,3,3] row_mask:0xf bank_mask:0xf bound_ctrl:1
	v_fmac_f32_dpp v10, v41, v5 quad_perm:[1,1,3,3] row_mask:0xf bank_mask:0xf bound_ctrl:1
	v_mul_f32_dpp v9, v65, v124 quad_perm:[1,1,3,3] row_mask:0xf bank_mask:0xf bound_ctrl:1
	v_fmac_f32_dpp v6, v48, v2 quad_perm:[0,0,2,2] row_mask:0xf bank_mask:0xf bound_ctrl:1
	v_add_f32_dpp v10, v10, v10 quad_perm:[2,3,0,1] row_mask:0xf bank_mask:0xf bound_ctrl:1
	v_fmac_f32_dpp v7, v49, v3 quad_perm:[0,0,2,2] row_mask:0xf bank_mask:0xf bound_ctrl:1
	v_fmac_f32_dpp v8, v48, v4 quad_perm:[1,1,3,3] row_mask:0xf bank_mask:0xf bound_ctrl:1
	v_add_f32_dpp v10, v10, v10 row_ror:4 row_mask:0xf bank_mask:0xf bound_ctrl:1
	v_fmac_f32_dpp v9, v49, v5 quad_perm:[1,1,3,3] row_mask:0xf bank_mask:0xf bound_ctrl:1
	v_mul_f32_dpp v13, v78, v2 quad_perm:[0,0,2,2] row_mask:0xf bank_mask:0xf bound_ctrl:1
	v_add_f32_dpp v10, v10, v10 row_ror:8 row_mask:0xf bank_mask:0xf bound_ctrl:1
	v_mov_b32_e32 v14, v10
	v_fmac_f32_dpp v13, v79, v3 quad_perm:[0,0,2,2] row_mask:0xf bank_mask:0xf bound_ctrl:1
	v_fmac_f32_dpp v13, v78, v4 quad_perm:[1,1,3,3] row_mask:0xf bank_mask:0xf bound_ctrl:1
	v_permlane16_swap_b32 v10, v14
	v_add_f32_e32 v10, v10, v14
	v_fmac_f32_dpp v6, v56, v10 quad_perm:[0,0,2,2] row_mask:0xf bank_mask:0xf bound_ctrl:1
	v_fmac_f32_dpp v7, v57, v10 quad_perm:[0,0,2,2] row_mask:0xf bank_mask:0xf bound_ctrl:1
	v_fmac_f32_dpp v8, v56, v10 quad_perm:[1,1,3,3] row_mask:0xf bank_mask:0xf bound_ctrl:1
	v_fmac_f32_dpp v9, v57, v10 quad_perm:[1,1,3,3] row_mask:0xf bank_mask:0xf bound_ctrl:1
	v_fmac_f32_dpp v13, v79, v5 quad_perm:[1,1,3,3] row_mask:0xf bank_mask:0xf bound_ctrl:1
	ds_write2st64_b32 v30, v12, v13 offset0:2 offset1:3
	ds_read_b64 v[44:45], v35 offset:26112
	ds_read_b64 v[52:53], v35 offset:9728
	ds_read_b64 v[60:61], v35 offset:34304
	ds_read_b64 v[68:69], v35 offset:17920
	ds_read_b64 v[76:77], v35 offset:1536
	ds_read2_b32 v[120:121], v37 offset0:96 offset1:112
	s_waitcnt lgkmcnt(7)
; __device__ __forceinline__ float allreduce16(float x) { x += dppf(x, 0); x += dppf(x, 1); x += dppf(x, 2); x += dppf(x, 3); return x; }
; __device__ void rw_scan(const Params& p, int l, unsigned char* shm, int item) {
;     ...
;                 for (int s2 = 0; s2 < 16; ++s2) {
;                     const int s = hs * 16 + s2, sn = (s + 1) & (TC - 1);
;                     const f32x4 na4 = *(const f32x4*)(sr + 3 * 2048 + sn * 64), nw4 = *(const f32x4*)(sr + 2048 + sn * 64), nb4 = *(const f32x4*)(sr + 4 * 2048 + sn * 64), nk4 = *(const f32x4*)(sr + 2 * 2048 + sn * 64), nr4 = *(const f32x4*)(sr + sn * 64);
;                     const float nvv = sv[sn * 16];
;                     f32x2 tq = S01 * (f32x2){a4[0], a4[1]}; tq = S23 * (f32x2){a4[2], a4[3]} + tq;
;                     const float sav = allreduce16(tq[0] + tq[1]);
;                     f32x2 u0 = (f32x2){b4[0], b4[1]} * sav, u1 = (f32x2){b4[2], b4[3]} * sav;
;                     u0 = (f32x2){k4[0], k4[1]} * vv + u0; u1 = (f32x2){k4[2], k4[3]} * vv + u1;
;                     S01 = S01 * (f32x2){w4[0], w4[1]} + u0; S23 = S23 * (f32x2){w4[2], w4[3]} + u1;
;                     f32x2 oq = S01 * (f32x2){r4[0], r4[1]}; oq = S23 * (f32x2){r4[2], r4[3]} + oq;
;                     pp[s2 * 64] = oq[0] + oq[1];
;                     a4 = na4; w4 = nw4; b4 = nb4; k4 = nk4; r4 = nr4; vv = nvv;
;                 }
	v_mul_f32_dpp v11, v42, v6 quad_perm:[0,0,2,2] row_mask:0xf bank_mask:0xf bound_ctrl:1
	v_mul_f32_dpp v2, v66, v125 quad_perm:[0,0,2,2] row_mask:0xf bank_mask:0xf bound_ctrl:1
	v_fmac_f32_dpp v11, v43, v7 quad_perm:[0,0,2,2] row_mask:0xf bank_mask:0xf bound_ctrl:1
	v_mul_f32_dpp v3, v67, v125 quad_perm:[0,0,2,2] row_mask:0xf bank_mask:0xf bound_ctrl:1
	v_fmac_f32_dpp v11, v42, v8 quad_perm:[1,1,3,3] row_mask:0xf bank_mask:0xf bound_ctrl:1
	v_mul_f32_dpp v4, v66, v125 quad_perm:[1,1,3,3] row_mask:0xf bank_mask:0xf bound_ctrl:1
	v_fmac_f32_dpp v11, v43, v9 quad_perm:[1,1,3,3] row_mask:0xf bank_mask:0xf bound_ctrl:1
	v_mul_f32_dpp v5, v67, v125 quad_perm:[1,1,3,3] row_mask:0xf bank_mask:0xf bound_ctrl:1
	v_fmac_f32_dpp v2, v50, v6 quad_perm:[0,0,2,2] row_mask:0xf bank_mask:0xf bound_ctrl:1
	v_add_f32_dpp v11, v11, v11 quad_perm:[2,3,0,1] row_mask:0xf bank_mask:0xf bound_ctrl:1
	v_fmac_f32_dpp v3, v51, v7 quad_perm:[0,0,2,2] row_mask:0xf bank_mask:0xf bound_ctrl:1
	v_fmac_f32_dpp v4, v50, v8 quad_perm:[1,1,3,3] row_mask:0xf bank_mask:0xf bound_ctrl:1
	v_add_f32_dpp v11, v11, v11 row_ror:4 row_mask:0xf bank_mask:0xf bound_ctrl:1
	v_fmac_f32_dpp v5, v51, v9 quad_perm:[1,1,3,3] row_mask:0xf bank_mask:0xf bound_ctrl:1
	v_mul_f32_dpp v12, v72, v6 quad_perm:[0,0,2,2] row_mask:0xf bank_mask:0xf bound_ctrl:1
	v_add_f32_dpp v11, v11, v11 row_ror:8 row_mask:0xf bank_mask:0xf bound_ctrl:1
	v_mov_b32_e32 v15, v11
	v_fmac_f32_dpp v12, v73, v7 quad_perm:[0,0,2,2] row_mask:0xf bank_mask:0xf bound_ctrl:1
	v_fmac_f32_dpp v12, v72, v8 quad_perm:[1,1,3,3] row_mask:0xf bank_mask:0xf bound_ctrl:1
	v_permlane16_swap_b32 v11, v15
	v_add_f32_e32 v11, v11, v15
	v_fmac_f32_dpp v2, v58, v11 quad_perm:[0,0,2,2] row_mask:0xf bank_mask:0xf bound_ctrl:1
	v_fmac_f32_dpp v3, v59, v11 quad_perm:[0,0,2,2] row_mask:0xf bank_mask:0xf bound_ctrl:1
	v_fmac_f32_dpp v4, v58, v11 quad_perm:[1,1,3,3] row_mask:0xf bank_mask:0xf bound_ctrl:1
	v_fmac_f32_dpp v5, v59, v11 quad_perm:[1,1,3,3] row_mask:0xf bank_mask:0xf bound_ctrl:1
	v_fmac_f32_dpp v12, v73, v9 quad_perm:[1,1,3,3] row_mask:0xf bank_mask:0xf bound_ctrl:1
	ds_read_b64 v[46:47], v35 offset:26368
	ds_read_b64 v[54:55], v35 offset:9984
	ds_read_b64 v[62:63], v35 offset:34560
	ds_read_b64 v[70:71], v35 offset:18176
	ds_read_b64 v[78:79], v35 offset:1792
	s_waitcnt lgkmcnt(5)
	v_mul_f32_dpp v10, v44, v2 quad_perm:[0,0,2,2] row_mask:0xf bank_mask:0xf bound_ctrl:1
	v_mul_f32_dpp v6, v68, v120 quad_perm:[0,0,2,2] row_mask:0xf bank_mask:0xf bound_ctrl:1
	v_fmac_f32_dpp v10, v45, v3 quad_perm:[0,0,2,2] row_mask:0xf bank_mask:0xf bound_ctrl:1
	v_mul_f32_dpp v7, v69, v120 quad_perm:[0,0,2,2] row_mask:0xf bank_mask:0xf bound_ctrl:1
	v_fmac_f32_dpp v10, v44, v4 quad_perm:[1,1,3,3] row_mask:0xf bank_mask:0xf bound_ctrl:1
	v_mul_f32_dpp v8, v68, v120 quad_perm:[1,1,3,3] row_mask:0xf bank_mask:0xf bound_ctrl:1
	v_fmac_f32_dpp v10, v45, v5 quad_perm:[1,1,3,3] row_mask:0xf bank_mask:0xf bound_ctrl:1
	v_mul_f32_dpp v9, v69, v120 quad_perm:[1,1,3,3] row_mask:0xf bank_mask:0xf bound_ctrl:1
	v_fmac_f32_dpp v6, v52, v2 quad_perm:[0,0,2,2] row_mask:0xf bank_mask:0xf bound_ctrl:1
	v_add_f32_dpp v10, v10, v10 quad_perm:[2,3,0,1] row_mask:0xf bank_mask:0xf bound_ctrl:1
	v_fmac_f32_dpp v7, v53, v3 quad_perm:[0,0,2,2] row_mask:0xf bank_mask:0xf bound_ctrl:1
	v_fmac_f32_dpp v8, v52, v4 quad_perm:[1,1,3,3] row_mask:0xf bank_mask:0xf bound_ctrl:1
	v_add_f32_dpp v10, v10, v10 row_ror:4 row_mask:0xf bank_mask:0xf bound_ctrl:1
	v_fmac_f32_dpp v9, v53, v5 quad_perm:[1,1,3,3] row_mask:0xf bank_mask:0xf bound_ctrl:1
	v_mul_f32_dpp v13, v74, v2 quad_perm:[0,0,2,2] row_mask:0xf bank_mask:0xf bound_ctrl:1
	v_add_f32_dpp v10, v10, v10 row_ror:8 row_mask:0xf bank_mask:0xf bound_ctrl:1
	v_mov_b32_e32 v14, v10
	v_fmac_f32_dpp v13, v75, v3 quad_perm:[0,0,2,2] row_mask:0xf bank_mask:0xf bound_ctrl:1
	v_fmac_f32_dpp v13, v74, v4 quad_perm:[1,1,3,3] row_mask:0xf bank_mask:0xf bound_ctrl:1
	v_permlane16_swap_b32 v10, v14
	v_add_f32_e32 v10, v10, v14
	v_fmac_f32_dpp v6, v60, v10 quad_perm:[0,0,2,2] row_mask:0xf bank_mask:0xf bound_ctrl:1
	v_fmac_f32_dpp v7, v61, v10 quad_perm:[0,0,2,2] row_mask:0xf bank_mask:0xf bound_ctrl:1
	v_fmac_f32_dpp v8, v60, v10 quad_perm:[1,1,3,3] row_mask:0xf bank_mask:0xf bound_ctrl:1
	v_fmac_f32_dpp v9, v61, v10 quad_perm:[1,1,3,3] row_mask:0xf bank_mask:0xf bound_ctrl:1
	v_fmac_f32_dpp v13, v75, v5 quad_perm:[1,1,3,3] row_mask:0xf bank_mask:0xf bound_ctrl:1
	ds_write2st64_b32 v30, v12, v13 offset0:4 offset1:5
	ds_read_b64 v[40:41], v35 offset:26624
	ds_read_b64 v[48:49], v35 offset:10240
	ds_read_b64 v[56:57], v35 offset:34816
	ds_read_b64 v[64:65], v35 offset:18432
	ds_read_b64 v[72:73], v35 offset:2048
	ds_read2_b32 v[122:123], v37 offset0:128 offset1:144
	s_waitcnt lgkmcnt(7)
; __device__ __forceinline__ float allreduce16(float x) { x += dppf(x, 0); x += dppf(x, 1); x += dppf(x, 2); x += dppf(x, 3); return x; }
; __device__ void rw_scan(const Params& p, int l, unsigned char* shm, int item) {
;     ...
;                 for (int s2 = 0; s2 < 16; ++s2) {
;                     const int s = hs * 16 + s2, sn = (s + 1) & (TC - 1);
;                     const f32x4 na4 = *(const f32x4*)(sr + 3 * 2048 + sn * 64), nw4 = *(const f32x4*)(sr + 2048 + sn * 64), nb4 = *(const f32x4*)(sr + 4 * 2048 + sn * 64), nk4 = *(const f32x4*)(sr + 2 * 2048 + sn * 64), nr4 = *(const f32x4*)(sr + sn * 64);
;                     const float nvv = sv[sn * 16];
;                     f32x2 tq = S01 * (f32x2){a4[0], a4[1]}; tq = S23 * (f32x2){a4[2], a4[3]} + tq;
;                     const float sav = allreduce16(tq[0] + tq[1]);
;                     f32x2 u0 = (f32x2){b4[0], b4[1]} * sav, u1 = (f32x2){b4[2], b4[3]} * sav;
;                     u0 = (f32x2){k4[0], k4[1]} * vv + u0; u1 = (f32x2){k4[2], k4[3]} * vv + u1;
;                     S01 = S01 * (f32x2){w4[0], w4[1]} + u0; S23 = S23 * (f32x2){w4[2], w4[3]} + u1;
;                     f32x2 oq = S01 * (f32x2){r4[0], r4[1]}; oq = S23 * (f32x2){r4[2], r4[3]} + oq;
;                     pp[s2 * 64] = oq[0] + oq[1];
;                     a4 = na4; w4 = nw4; b4 = nb4; k4 = nk4; r4 = nr4; vv = nvv;
;                 }
	v_mul_f32_dpp v11, v46, v6 quad_perm:[0,0,2,2] row_mask:0xf bank_mask:0xf bound_ctrl:1
	v_mul_f32_dpp v2, v70, v121 quad_perm:[0,0,2,2] row_mask:0xf bank_mask:0xf bound_ctrl:1
	v_fmac_f32_dpp v11, v47, v7 quad_perm:[0,0,2,2] row_mask:0xf bank_mask:0xf bound_ctrl:1
	v_mul_f32_dpp v3, v71, v121 quad_perm:[0,0,2,2] row_mask:0xf bank_mask:0xf bound_ctrl:1
	v_fmac_f32_dpp v11, v46, v8 quad_perm:[1,1,3,3] row_mask:0xf bank_mask:0xf bound_ctrl:1
	v_mul_f32_dpp v4, v70, v121 quad_perm:[1,1,3,3] row_mask:0xf bank_mask:0xf bound_ctrl:1
	v_fmac_f32_dpp v11, v47, v9 quad_perm:[1,1,3,3] row_mask:0xf bank_mask:0xf bound_ctrl:1
	v_mul_f32_dpp v5, v71, v121 quad_perm:[1,1,3,3] row_mask:0xf bank_mask:0xf bound_ctrl:1
	v_fmac_f32_dpp v2, v54, v6 quad_perm:[0,0,2,2] row_mask:0xf bank_mask:0xf bound_ctrl:1
	v_add_f32_dpp v11, v11, v11 quad_perm:[2,3,0,1] row_mask:0xf bank_mask:0xf bound_ctrl:1
	v_fmac_f32_dpp v3, v55, v7 quad_perm:[0,0,2,2] row_mask:0xf bank_mask:0xf bound_ctrl:1
	v_fmac_f32_dpp v4, v54, v8 quad_perm:[1,1,3,3] row_mask:0xf bank_mask:0xf bound_ctrl:1
	v_add_f32_dpp v11, v11, v11 row_ror:4 row_mask:0xf bank_mask:0xf bound_ctrl:1
	v_fmac_f32_dpp v5, v55, v9 quad_perm:[1,1,3,3] row_mask:0xf bank_mask:0xf bound_ctrl:1
	v_mul_f32_dpp v12, v76, v6 quad_perm:[0,0,2,2] row_mask:0xf bank_mask:0xf bound_ctrl:1
	v_add_f32_dpp v11, v11, v11 row_ror:8 row_mask:0xf bank_mask:0xf bound_ctrl:1
	v_mov_b32_e32 v15, v11
	v_fmac_f32_dpp v12, v77, v7 quad_perm:[0,0,2,2] row_mask:0xf bank_mask:0xf bound_ctrl:1
	v_fmac_f32_dpp v12, v76, v8 quad_perm:[1,1,3,3] row_mask:0xf bank_mask:0xf bound_ctrl:1
	v_permlane16_swap_b32 v11, v15
	v_add_f32_e32 v11, v11, v15
	v_fmac_f32_dpp v2, v62, v11 quad_perm:[0,0,2,2] row_mask:0xf bank_mask:0xf bound_ctrl:1
	v_fmac_f32_dpp v3, v63, v11 quad_perm:[0,0,2,2] row_mask:0xf bank_mask:0xf bound_ctrl:1
	v_fmac_f32_dpp v4, v62, v11 quad_perm:[1,1,3,3] row_mask:0xf bank_mask:0xf bound_ctrl:1
	v_fmac_f32_dpp v5, v63, v11 quad_perm:[1,1,3,3] row_mask:0xf bank_mask:0xf bound_ctrl:1
	v_fmac_f32_dpp v12, v77, v9 quad_perm:[1,1,3,3] row_mask:0xf bank_mask:0xf bound_ctrl:1
	ds_read_b64 v[42:43], v35 offset:26880
	ds_read_b64 v[50:51], v35 offset:10496
	ds_read_b64 v[58:59], v35 offset:35072
	ds_read_b64 v[66:67], v35 offset:18688
	ds_read_b64 v[74:75], v35 offset:2304
	s_waitcnt lgkmcnt(5)
	v_mul_f32_dpp v10, v40, v2 quad_perm:[0,0,2,2] row_mask:0xf bank_mask:0xf bound_ctrl:1
	v_mul_f32_dpp v6, v64, v122 quad_perm:[0,0,2,2] row_mask:0xf bank_mask:0xf bound_ctrl:1
	v_fmac_f32_dpp v10, v41, v3 quad_perm:[0,0,2,2] row_mask:0xf bank_mask:0xf bound_ctrl:1
	v_mul_f32_dpp v7, v65, v122 quad_perm:[0,0,2,2] row_mask:0xf bank_mask:0xf bound_ctrl:1
	v_fmac_f32_dpp v10, v40, v4 quad_perm:[1,1,3,3] row_mask:0xf bank_mask:0xf bound_ctrl:1
	v_mul_f32_dpp v8, v64, v122 quad_perm:[1,1,3,3] row_mask:0xf bank_mask:0xf bound_ctrl:1
	v_fmac_f32_dpp v10, v41, v5 quad_perm:[1,1,3,3] row_mask:0xf bank_mask:0xf bound_ctrl:1
	v_mul_f32_dpp v9, v65, v122 quad_perm:[1,1,3,3] row_mask:0xf bank_mask:0xf bound_ctrl:1
	v_fmac_f32_dpp v6, v48, v2 quad_perm:[0,0,2,2] row_mask:0xf bank_mask:0xf bound_ctrl:1
	v_add_f32_dpp v10, v10, v10 quad_perm:[2,3,0,1] row_mask:0xf bank_mask:0xf bound_ctrl:1
	v_fmac_f32_dpp v7, v49, v3 quad_perm:[0,0,2,2] row_mask:0xf bank_mask:0xf bound_ctrl:1
	v_fmac_f32_dpp v8, v48, v4 quad_perm:[1,1,3,3] row_mask:0xf bank_mask:0xf bound_ctrl:1
	v_add_f32_dpp v10, v10, v10 row_ror:4 row_mask:0xf bank_mask:0xf bound_ctrl:1
	v_fmac_f32_dpp v9, v49, v5 quad_perm:[1,1,3,3] row_mask:0xf bank_mask:0xf bound_ctrl:1
	v_mul_f32_dpp v13, v78, v2 quad_perm:[0,0,2,2] row_mask:0xf bank_mask:0xf bound_ctrl:1
	v_add_f32_dpp v10, v10, v10 row_ror:8 row_mask:0xf bank_mask:0xf bound_ctrl:1
	v_mov_b32_e32 v14, v10
	v_fmac_f32_dpp v13, v79, v3 quad_perm:[0,0,2,2] row_mask:0xf bank_mask:0xf bound_ctrl:1
	v_fmac_f32_dpp v13, v78, v4 quad_perm:[1,1,3,3] row_mask:0xf bank_mask:0xf bound_ctrl:1
	v_permlane16_swap_b32 v10, v14
	v_add_f32_e32 v10, v10, v14
	v_fmac_f32_dpp v6, v56, v10 quad_perm:[0,0,2,2] row_mask:0xf bank_mask:0xf bound_ctrl:1
	v_fmac_f32_dpp v7, v57, v10 quad_perm:[0,0,2,2] row_mask:0xf bank_mask:0xf bound_ctrl:1
	v_fmac_f32_dpp v8, v56, v10 quad_perm:[1,1,3,3] row_mask:0xf bank_mask:0xf bound_ctrl:1
	v_fmac_f32_dpp v9, v57, v10 quad_perm:[1,1,3,3] row_mask:0xf bank_mask:0xf bound_ctrl:1
	v_fmac_f32_dpp v13, v79, v5 quad_perm:[1,1,3,3] row_mask:0xf bank_mask:0xf bound_ctrl:1
	ds_write2st64_b32 v30, v12, v13 offset0:6 offset1:7
	ds_read_b64 v[44:45], v35 offset:27136
	ds_read_b64 v[52:53], v35 offset:10752
	ds_read_b64 v[60:61], v35 offset:35328
	ds_read_b64 v[68:69], v35 offset:18944
	ds_read_b64 v[76:77], v35 offset:2560
	ds_read2_b32 v[124:125], v37 offset0:160 offset1:176
	s_waitcnt lgkmcnt(7)
; __device__ __forceinline__ float allreduce16(float x) { x += dppf(x, 0); x += dppf(x, 1); x += dppf(x, 2); x += dppf(x, 3); return x; }
; __device__ void rw_scan(const Params& p, int l, unsigned char* shm, int item) {
;     ...
;                 for (int s2 = 0; s2 < 16; ++s2) {
;                     const int s = hs * 16 + s2, sn = (s + 1) & (TC - 1);
;                     const f32x4 na4 = *(const f32x4*)(sr + 3 * 2048 + sn * 64), nw4 = *(const f32x4*)(sr + 2048 + sn * 64), nb4 = *(const f32x4*)(sr + 4 * 2048 + sn * 64), nk4 = *(const f32x4*)(sr + 2 * 2048 + sn * 64), nr4 = *(const f32x4*)(sr + sn * 64);
;                     const float nvv = sv[sn * 16];
;                     f32x2 tq = S01 * (f32x2){a4[0], a4[1]}; tq = S23 * (f32x2){a4[2], a4[3]} + tq;
;                     const float sav = allreduce16(tq[0] + tq[1]);
;                     f32x2 u0 = (f32x2){b4[0], b4[1]} * sav, u1 = (f32x2){b4[2], b4[3]} * sav;
;                     u0 = (f32x2){k4[0], k4[1]} * vv + u0; u1 = (f32x2){k4[2], k4[3]} * vv + u1;
;                     S01 = S01 * (f32x2){w4[0], w4[1]} + u0; S23 = S23 * (f32x2){w4[2], w4[3]} + u1;
;                     f32x2 oq = S01 * (f32x2){r4[0], r4[1]}; oq = S23 * (f32x2){r4[2], r4[3]} + oq;
;                     pp[s2 * 64] = oq[0] + oq[1];
;                     a4 = na4; w4 = nw4; b4 = nb4; k4 = nk4; r4 = nr4; vv = nvv;
;                 }
	v_mul_f32_dpp v11, v42, v6 quad_perm:[0,0,2,2] row_mask:0xf bank_mask:0xf bound_ctrl:1
	v_mul_f32_dpp v2, v66, v123 quad_perm:[0,0,2,2] row_mask:0xf bank_mask:0xf bound_ctrl:1
	v_fmac_f32_dpp v11, v43, v7 quad_perm:[0,0,2,2] row_mask:0xf bank_mask:0xf bound_ctrl:1
	v_mul_f32_dpp v3, v67, v123 quad_perm:[0,0,2,2] row_mask:0xf bank_mask:0xf bound_ctrl:1
	v_fmac_f32_dpp v11, v42, v8 quad_perm:[1,1,3,3] row_mask:0xf bank_mask:0xf bound_ctrl:1
	v_mul_f32_dpp v4, v66, v123 quad_perm:[1,1,3,3] row_mask:0xf bank_mask:0xf bound_ctrl:1
	v_fmac_f32_dpp v11, v43, v9 quad_perm:[1,1,3,3] row_mask:0xf bank_mask:0xf bound_ctrl:1
	v_mul_f32_dpp v5, v67, v123 quad_perm:[1,1,3,3] row_mask:0xf bank_mask:0xf bound_ctrl:1
	v_fmac_f32_dpp v2, v50, v6 quad_perm:[0,0,2,2] row_mask:0xf bank_mask:0xf bound_ctrl:1
	v_add_f32_dpp v11, v11, v11 quad_perm:[2,3,0,1] row_mask:0xf bank_mask:0xf bound_ctrl:1
	v_fmac_f32_dpp v3, v51, v7 quad_perm:[0,0,2,2] row_mask:0xf bank_mask:0xf bound_ctrl:1
	v_fmac_f32_dpp v4, v50, v8 quad_perm:[1,1,3,3] row_mask:0xf bank_mask:0xf bound_ctrl:1
	v_add_f32_dpp v11, v11, v11 row_ror:4 row_mask:0xf bank_mask:0xf bound_ctrl:1
	v_fmac_f32_dpp v5, v51, v9 quad_perm:[1,1,3,3] row_mask:0xf bank_mask:0xf bound_ctrl:1
	v_mul_f32_dpp v12, v72, v6 quad_perm:[0,0,2,2] row_mask:0xf bank_mask:0xf bound_ctrl:1
	v_add_f32_dpp v11, v11, v11 row_ror:8 row_mask:0xf bank_mask:0xf bound_ctrl:1
	v_mov_b32_e32 v15, v11
	v_fmac_f32_dpp v12, v73, v7 quad_perm:[0,0,2,2] row_mask:0xf bank_mask:0xf bound_ctrl:1
	v_fmac_f32_dpp v12, v72, v8 quad_perm:[1,1,3,3] row_mask:0xf bank_mask:0xf bound_ctrl:1
	v_permlane16_swap_b32 v11, v15
	v_add_f32_e32 v11, v11, v15
	v_fmac_f32_dpp v2, v58, v11 quad_perm:[0,0,2,2] row_mask:0xf bank_mask:0xf bound_ctrl:1
	v_fmac_f32_dpp v3, v59, v11 quad_perm:[0,0,2,2] row_mask:0xf bank_mask:0xf bound_ctrl:1
	v_fmac_f32_dpp v4, v58, v11 quad_perm:[1,1,3,3] row_mask:0xf bank_mask:0xf bound_ctrl:1
	v_fmac_f32_dpp v5, v59, v11 quad_perm:[1,1,3,3] row_mask:0xf bank_mask:0xf bound_ctrl:1
	v_fmac_f32_dpp v12, v73, v9 quad_perm:[1,1,3,3] row_mask:0xf bank_mask:0xf bound_ctrl:1
	ds_read_b64 v[46:47], v35 offset:27392
	ds_read_b64 v[54:55], v35 offset:11008
	ds_read_b64 v[62:63], v35 offset:35584
	ds_read_b64 v[70:71], v35 offset:19200
	ds_read_b64 v[78:79], v35 offset:2816
	s_waitcnt lgkmcnt(5)
	v_mul_f32_dpp v10, v44, v2 quad_perm:[0,0,2,2] row_mask:0xf bank_mask:0xf bound_ctrl:1
	v_mul_f32_dpp v6, v68, v124 quad_perm:[0,0,2,2] row_mask:0xf bank_mask:0xf bound_ctrl:1
	v_fmac_f32_dpp v10, v45, v3 quad_perm:[0,0,2,2] row_mask:0xf bank_mask:0xf bound_ctrl:1
	v_mul_f32_dpp v7, v69, v124 quad_perm:[0,0,2,2] row_mask:0xf bank_mask:0xf bound_ctrl:1
	v_fmac_f32_dpp v10, v44, v4 quad_perm:[1,1,3,3] row_mask:0xf bank_mask:0xf bound_ctrl:1
	v_mul_f32_dpp v8, v68, v124 quad_perm:[1,1,3,3] row_mask:0xf bank_mask:0xf bound_ctrl:1
	v_fmac_f32_dpp v10, v45, v5 quad_perm:[1,1,3,3] row_mask:0xf bank_mask:0xf bound_ctrl:1
	v_mul_f32_dpp v9, v69, v124 quad_perm:[1,1,3,3] row_mask:0xf bank_mask:0xf bound_ctrl:1
	v_fmac_f32_dpp v6, v52, v2 quad_perm:[0,0,2,2] row_mask:0xf bank_mask:0xf bound_ctrl:1
	v_add_f32_dpp v10, v10, v10 quad_perm:[2,3,0,1] row_mask:0xf bank_mask:0xf bound_ctrl:1
	v_fmac_f32_dpp v7, v53, v3 quad_perm:[0,0,2,2] row_mask:0xf bank_mask:0xf bound_ctrl:1
	v_fmac_f32_dpp v8, v52, v4 quad_perm:[1,1,3,3] row_mask:0xf bank_mask:0xf bound_ctrl:1
	v_add_f32_dpp v10, v10, v10 row_ror:4 row_mask:0xf bank_mask:0xf bound_ctrl:1
	v_fmac_f32_dpp v9, v53, v5 quad_perm:[1,1,3,3] row_mask:0xf bank_mask:0xf bound_ctrl:1
	v_mul_f32_dpp v13, v74, v2 quad_perm:[0,0,2,2] row_mask:0xf bank_mask:0xf bound_ctrl:1
	v_add_f32_dpp v10, v10, v10 row_ror:8 row_mask:0xf bank_mask:0xf bound_ctrl:1
	v_mov_b32_e32 v14, v10
	v_fmac_f32_dpp v13, v75, v3 quad_perm:[0,0,2,2] row_mask:0xf bank_mask:0xf bound_ctrl:1
	v_fmac_f32_dpp v13, v74, v4 quad_perm:[1,1,3,3] row_mask:0xf bank_mask:0xf bound_ctrl:1
	v_permlane16_swap_b32 v10, v14
	v_add_f32_e32 v10, v10, v14
	v_fmac_f32_dpp v6, v60, v10 quad_perm:[0,0,2,2] row_mask:0xf bank_mask:0xf bound_ctrl:1
	v_fmac_f32_dpp v7, v61, v10 quad_perm:[0,0,2,2] row_mask:0xf bank_mask:0xf bound_ctrl:1
	v_fmac_f32_dpp v8, v60, v10 quad_perm:[1,1,3,3] row_mask:0xf bank_mask:0xf bound_ctrl:1
	v_fmac_f32_dpp v9, v61, v10 quad_perm:[1,1,3,3] row_mask:0xf bank_mask:0xf bound_ctrl:1
	v_fmac_f32_dpp v13, v75, v5 quad_perm:[1,1,3,3] row_mask:0xf bank_mask:0xf bound_ctrl:1
	ds_write2st64_b32 v30, v12, v13 offset0:8 offset1:9
	ds_read_b64 v[40:41], v35 offset:27648
	ds_read_b64 v[48:49], v35 offset:11264
	ds_read_b64 v[56:57], v35 offset:35840
	ds_read_b64 v[64:65], v35 offset:19456
	ds_read_b64 v[72:73], v35 offset:3072
	ds_read2_b32 v[120:121], v37 offset0:192 offset1:208
	s_waitcnt lgkmcnt(7)
; __device__ __forceinline__ float allreduce16(float x) { x += dppf(x, 0); x += dppf(x, 1); x += dppf(x, 2); x += dppf(x, 3); return x; }
; __device__ void rw_scan(const Params& p, int l, unsigned char* shm, int item) {
;     ...
;                 for (int s2 = 0; s2 < 16; ++s2) {
;                     const int s = hs * 16 + s2, sn = (s + 1) & (TC - 1);
;                     const f32x4 na4 = *(const f32x4*)(sr + 3 * 2048 + sn * 64), nw4 = *(const f32x4*)(sr + 2048 + sn * 64), nb4 = *(const f32x4*)(sr + 4 * 2048 + sn * 64), nk4 = *(const f32x4*)(sr + 2 * 2048 + sn * 64), nr4 = *(const f32x4*)(sr + sn * 64);
;                     const float nvv = sv[sn * 16];
;                     f32x2 tq = S01 * (f32x2){a4[0], a4[1]}; tq = S23 * (f32x2){a4[2], a4[3]} + tq;
;                     const float sav = allreduce16(tq[0] + tq[1]);
;                     f32x2 u0 = (f32x2){b4[0], b4[1]} * sav, u1 = (f32x2){b4[2], b4[3]} * sav;
;                     u0 = (f32x2){k4[0], k4[1]} * vv + u0; u1 = (f32x2){k4[2], k4[3]} * vv + u1;
;                     S01 = S01 * (f32x2){w4[0], w4[1]} + u0; S23 = S23 * (f32x2){w4[2], w4[3]} + u1;
;                     f32x2 oq = S01 * (f32x2){r4[0], r4[1]}; oq = S23 * (f32x2){r4[2], r4[3]} + oq;
;                     pp[s2 * 64] = oq[0] + oq[1];
;                     a4 = na4; w4 = nw4; b4 = nb4; k4 = nk4; r4 = nr4; vv = nvv;
;                 }
	v_mul_f32_dpp v11, v46, v6 quad_perm:[0,0,2,2] row_mask:0xf bank_mask:0xf bound_ctrl:1
	v_mul_f32_dpp v2, v70, v125 quad_perm:[0,0,2,2] row_mask:0xf bank_mask:0xf bound_ctrl:1
	v_fmac_f32_dpp v11, v47, v7 quad_perm:[0,0,2,2] row_mask:0xf bank_mask:0xf bound_ctrl:1
	v_mul_f32_dpp v3, v71, v125 quad_perm:[0,0,2,2] row_mask:0xf bank_mask:0xf bound_ctrl:1
	v_fmac_f32_dpp v11, v46, v8 quad_perm:[1,1,3,3] row_mask:0xf bank_mask:0xf bound_ctrl:1
	v_mul_f32_dpp v4, v70, v125 quad_perm:[1,1,3,3] row_mask:0xf bank_mask:0xf bound_ctrl:1
	v_fmac_f32_dpp v11, v47, v9 quad_perm:[1,1,3,3] row_mask:0xf bank_mask:0xf bound_ctrl:1
	v_mul_f32_dpp v5, v71, v125 quad_perm:[1,1,3,3] row_mask:0xf bank_mask:0xf bound_ctrl:1
	v_fmac_f32_dpp v2, v54, v6 quad_perm:[0,0,2,2] row_mask:0xf bank_mask:0xf bound_ctrl:1
	v_add_f32_dpp v11, v11, v11 quad_perm:[2,3,0,1] row_mask:0xf bank_mask:0xf bound_ctrl:1
	v_fmac_f32_dpp v3, v55, v7 quad_perm:[0,0,2,2] row_mask:0xf bank_mask:0xf bound_ctrl:1
	v_fmac_f32_dpp v4, v54, v8 quad_perm:[1,1,3,3] row_mask:0xf bank_mask:0xf bound_ctrl:1
	v_add_f32_dpp v11, v11, v11 row_ror:4 row_mask:0xf bank_mask:0xf bound_ctrl:1
	v_fmac_f32_dpp v5, v55, v9 quad_perm:[1,1,3,3] row_mask:0xf bank_mask:0xf bound_ctrl:1
	v_mul_f32_dpp v12, v76, v6 quad_perm:[0,0,2,2] row_mask:0xf bank_mask:0xf bound_ctrl:1
	v_add_f32_dpp v11, v11, v11 row_ror:8 row_mask:0xf bank_mask:0xf bound_ctrl:1
	v_mov_b32_e32 v15, v11
	v_fmac_f32_dpp v12, v77, v7 quad_perm:[0,0,2,2] row_mask:0xf bank_mask:0xf bound_ctrl:1
	v_fmac_f32_dpp v12, v76, v8 quad_perm:[1,1,3,3] row_mask:0xf bank_mask:0xf bound_ctrl:1
	v_permlane16_swap_b32 v11, v15
	v_add_f32_e32 v11, v11, v15
	v_fmac_f32_dpp v2, v62, v11 quad_perm:[0,0,2,2] row_mask:0xf bank_mask:0xf bound_ctrl:1
	v_fmac_f32_dpp v3, v63, v11 quad_perm:[0,0,2,2] row_mask:0xf bank_mask:0xf bound_ctrl:1
	v_fmac_f32_dpp v4, v62, v11 quad_perm:[1,1,3,3] row_mask:0xf bank_mask:0xf bound_ctrl:1
	v_fmac_f32_dpp v5, v63, v11 quad_perm:[1,1,3,3] row_mask:0xf bank_mask:0xf bound_ctrl:1
	v_fmac_f32_dpp v12, v77, v9 quad_perm:[1,1,3,3] row_mask:0xf bank_mask:0xf bound_ctrl:1
	ds_read_b64 v[42:43], v35 offset:27904
	ds_read_b64 v[50:51], v35 offset:11520
	ds_read_b64 v[58:59], v35 offset:36096
	ds_read_b64 v[66:67], v35 offset:19712
	ds_read_b64 v[74:75], v35 offset:3328
	s_waitcnt lgkmcnt(5)
	v_mul_f32_dpp v10, v40, v2 quad_perm:[0,0,2,2] row_mask:0xf bank_mask:0xf bound_ctrl:1
	v_mul_f32_dpp v6, v64, v120 quad_perm:[0,0,2,2] row_mask:0xf bank_mask:0xf bound_ctrl:1
	v_fmac_f32_dpp v10, v41, v3 quad_perm:[0,0,2,2] row_mask:0xf bank_mask:0xf bound_ctrl:1
	v_mul_f32_dpp v7, v65, v120 quad_perm:[0,0,2,2] row_mask:0xf bank_mask:0xf bound_ctrl:1
	v_fmac_f32_dpp v10, v40, v4 quad_perm:[1,1,3,3] row_mask:0xf bank_mask:0xf bound_ctrl:1
	v_mul_f32_dpp v8, v64, v120 quad_perm:[1,1,3,3] row_mask:0xf bank_mask:0xf bound_ctrl:1
	v_fmac_f32_dpp v10, v41, v5 quad_perm:[1,1,3,3] row_mask:0xf bank_mask:0xf bound_ctrl:1
	v_mul_f32_dpp v9, v65, v120 quad_perm:[1,1,3,3] row_mask:0xf bank_mask:0xf bound_ctrl:1
	v_fmac_f32_dpp v6, v48, v2 quad_perm:[0,0,2,2] row_mask:0xf bank_mask:0xf bound_ctrl:1
	v_add_f32_dpp v10, v10, v10 quad_perm:[2,3,0,1] row_mask:0xf bank_mask:0xf bound_ctrl:1
	v_fmac_f32_dpp v7, v49, v3 quad_perm:[0,0,2,2] row_mask:0xf bank_mask:0xf bound_ctrl:1
	v_fmac_f32_dpp v8, v48, v4 quad_perm:[1,1,3,3] row_mask:0xf bank_mask:0xf bound_ctrl:1
	v_add_f32_dpp v10, v10, v10 row_ror:4 row_mask:0xf bank_mask:0xf bound_ctrl:1
	v_fmac_f32_dpp v9, v49, v5 quad_perm:[1,1,3,3] row_mask:0xf bank_mask:0xf bound_ctrl:1
	v_mul_f32_dpp v13, v78, v2 quad_perm:[0,0,2,2] row_mask:0xf bank_mask:0xf bound_ctrl:1
	v_add_f32_dpp v10, v10, v10 row_ror:8 row_mask:0xf bank_mask:0xf bound_ctrl:1
	v_mov_b32_e32 v14, v10
	v_fmac_f32_dpp v13, v79, v3 quad_perm:[0,0,2,2] row_mask:0xf bank_mask:0xf bound_ctrl:1
	v_fmac_f32_dpp v13, v78, v4 quad_perm:[1,1,3,3] row_mask:0xf bank_mask:0xf bound_ctrl:1
	v_permlane16_swap_b32 v10, v14
	v_add_f32_e32 v10, v10, v14
	v_fmac_f32_dpp v6, v56, v10 quad_perm:[0,0,2,2] row_mask:0xf bank_mask:0xf bound_ctrl:1
	v_fmac_f32_dpp v7, v57, v10 quad_perm:[0,0,2,2] row_mask:0xf bank_mask:0xf bound_ctrl:1
	v_fmac_f32_dpp v8, v56, v10 quad_perm:[1,1,3,3] row_mask:0xf bank_mask:0xf bound_ctrl:1
	v_fmac_f32_dpp v9, v57, v10 quad_perm:[1,1,3,3] row_mask:0xf bank_mask:0xf bound_ctrl:1
	v_fmac_f32_dpp v13, v79, v5 quad_perm:[1,1,3,3] row_mask:0xf bank_mask:0xf bound_ctrl:1
	ds_write2st64_b32 v30, v12, v13 offset0:10 offset1:11
	ds_read_b64 v[44:45], v35 offset:28160
	ds_read_b64 v[52:53], v35 offset:11776
	ds_read_b64 v[60:61], v35 offset:36352
	ds_read_b64 v[68:69], v35 offset:19968
	ds_read_b64 v[76:77], v35 offset:3584
	ds_read2_b32 v[122:123], v37 offset0:224 offset1:240
	s_waitcnt lgkmcnt(7)
; __device__ __forceinline__ float allreduce16(float x) { x += dppf(x, 0); x += dppf(x, 1); x += dppf(x, 2); x += dppf(x, 3); return x; }
; __device__ void rw_scan(const Params& p, int l, unsigned char* shm, int item) {
;     ...
;                 for (int s2 = 0; s2 < 16; ++s2) {
;                     const int s = hs * 16 + s2, sn = (s + 1) & (TC - 1);
;                     const f32x4 na4 = *(const f32x4*)(sr + 3 * 2048 + sn * 64), nw4 = *(const f32x4*)(sr + 2048 + sn * 64), nb4 = *(const f32x4*)(sr + 4 * 2048 + sn * 64), nk4 = *(const f32x4*)(sr + 2 * 2048 + sn * 64), nr4 = *(const f32x4*)(sr + sn * 64);
;                     const float nvv = sv[sn * 16];
;                     f32x2 tq = S01 * (f32x2){a4[0], a4[1]}; tq = S23 * (f32x2){a4[2], a4[3]} + tq;
;                     const float sav = allreduce16(tq[0] + tq[1]);
;                     f32x2 u0 = (f32x2){b4[0], b4[1]} * sav, u1 = (f32x2){b4[2], b4[3]} * sav;
;                     u0 = (f32x2){k4[0], k4[1]} * vv + u0; u1 = (f32x2){k4[2], k4[3]} * vv + u1;
;                     S01 = S01 * (f32x2){w4[0], w4[1]} + u0; S23 = S23 * (f32x2){w4[2], w4[3]} + u1;
;                     f32x2 oq = S01 * (f32x2){r4[0], r4[1]}; oq = S23 * (f32x2){r4[2], r4[3]} + oq;
;                     pp[s2 * 64] = oq[0] + oq[1];
;                     a4 = na4; w4 = nw4; b4 = nb4; k4 = nk4; r4 = nr4; vv = nvv;
	v_mul_f32_dpp v11, v42, v6 quad_perm:[0,0,2,2] row_mask:0xf bank_mask:0xf bound_ctrl:1
	v_mul_f32_dpp v2, v66, v121 quad_perm:[0,0,2,2] row_mask:0xf bank_mask:0xf bound_ctrl:1
	v_fmac_f32_dpp v11, v43, v7 quad_perm:[0,0,2,2] row_mask:0xf bank_mask:0xf bound_ctrl:1
	v_mul_f32_dpp v3, v67, v121 quad_perm:[0,0,2,2] row_mask:0xf bank_mask:0xf bound_ctrl:1
	v_fmac_f32_dpp v11, v42, v8 quad_perm:[1,1,3,3] row_mask:0xf bank_mask:0xf bound_ctrl:1
	v_mul_f32_dpp v4, v66, v121 quad_perm:[1,1,3,3] row_mask:0xf bank_mask:0xf bound_ctrl:1
	v_fmac_f32_dpp v11, v43, v9 quad_perm:[1,1,3,3] row_mask:0xf bank_mask:0xf bound_ctrl:1
	v_mul_f32_dpp v5, v67, v121 quad_perm:[1,1,3,3] row_mask:0xf bank_mask:0xf bound_ctrl:1
	v_fmac_f32_dpp v2, v50, v6 quad_perm:[0,0,2,2] row_mask:0xf bank_mask:0xf bound_ctrl:1
	v_add_f32_dpp v11, v11, v11 quad_perm:[2,3,0,1] row_mask:0xf bank_mask:0xf bound_ctrl:1
	v_fmac_f32_dpp v3, v51, v7 quad_perm:[0,0,2,2] row_mask:0xf bank_mask:0xf bound_ctrl:1
	v_fmac_f32_dpp v4, v50, v8 quad_perm:[1,1,3,3] row_mask:0xf bank_mask:0xf bound_ctrl:1
	v_add_f32_dpp v11, v11, v11 row_ror:4 row_mask:0xf bank_mask:0xf bound_ctrl:1
	v_fmac_f32_dpp v5, v51, v9 quad_perm:[1,1,3,3] row_mask:0xf bank_mask:0xf bound_ctrl:1
	v_mul_f32_dpp v12, v72, v6 quad_perm:[0,0,2,2] row_mask:0xf bank_mask:0xf bound_ctrl:1
	v_add_f32_dpp v11, v11, v11 row_ror:8 row_mask:0xf bank_mask:0xf bound_ctrl:1
	v_mov_b32_e32 v15, v11
	v_fmac_f32_dpp v12, v73, v7 quad_perm:[0,0,2,2] row_mask:0xf bank_mask:0xf bound_ctrl:1
	v_fmac_f32_dpp v12, v72, v8 quad_perm:[1,1,3,3] row_mask:0xf bank_mask:0xf bound_ctrl:1
	v_permlane16_swap_b32 v11, v15
	v_add_f32_e32 v11, v11, v15
	v_fmac_f32_dpp v2, v58, v11 quad_perm:[0,0,2,2] row_mask:0xf bank_mask:0xf bound_ctrl:1
	v_fmac_f32_dpp v3, v59, v11 quad_perm:[0,0,2,2] row_mask:0xf bank_mask:0xf bound_ctrl:1
	v_fmac_f32_dpp v4, v58, v11 quad_perm:[1,1,3,3] row_mask:0xf bank_mask:0xf bound_ctrl:1
	v_fmac_f32_dpp v5, v59, v11 quad_perm:[1,1,3,3] row_mask:0xf bank_mask:0xf bound_ctrl:1
	v_fmac_f32_dpp v12, v73, v9 quad_perm:[1,1,3,3] row_mask:0xf bank_mask:0xf bound_ctrl:1
	ds_read_b64 v[46:47], v35 offset:28416
	ds_read_b64 v[54:55], v35 offset:12032
	ds_read_b64 v[62:63], v35 offset:36608
	ds_read_b64 v[70:71], v35 offset:20224
	ds_read_b64 v[78:79], v35 offset:3840
	s_waitcnt lgkmcnt(5)
	v_mul_f32_dpp v10, v44, v2 quad_perm:[0,0,2,2] row_mask:0xf bank_mask:0xf bound_ctrl:1
	v_mul_f32_dpp v6, v68, v122 quad_perm:[0,0,2,2] row_mask:0xf bank_mask:0xf bound_ctrl:1
	v_fmac_f32_dpp v10, v45, v3 quad_perm:[0,0,2,2] row_mask:0xf bank_mask:0xf bound_ctrl:1
	v_mul_f32_dpp v7, v69, v122 quad_perm:[0,0,2,2] row_mask:0xf bank_mask:0xf bound_ctrl:1
	v_fmac_f32_dpp v10, v44, v4 quad_perm:[1,1,3,3] row_mask:0xf bank_mask:0xf bound_ctrl:1
	v_mul_f32_dpp v8, v68, v122 quad_perm:[1,1,3,3] row_mask:0xf bank_mask:0xf bound_ctrl:1
	v_fmac_f32_dpp v10, v45, v5 quad_perm:[1,1,3,3] row_mask:0xf bank_mask:0xf bound_ctrl:1
	v_mul_f32_dpp v9, v69, v122 quad_perm:[1,1,3,3] row_mask:0xf bank_mask:0xf bound_ctrl:1
	v_fmac_f32_dpp v6, v52, v2 quad_perm:[0,0,2,2] row_mask:0xf bank_mask:0xf bound_ctrl:1
	v_add_f32_dpp v10, v10, v10 quad_perm:[2,3,0,1] row_mask:0xf bank_mask:0xf bound_ctrl:1
	v_fmac_f32_dpp v7, v53, v3 quad_perm:[0,0,2,2] row_mask:0xf bank_mask:0xf bound_ctrl:1
	v_fmac_f32_dpp v8, v52, v4 quad_perm:[1,1,3,3] row_mask:0xf bank_mask:0xf bound_ctrl:1
	v_add_f32_dpp v10, v10, v10 row_ror:4 row_mask:0xf bank_mask:0xf bound_ctrl:1
	v_fmac_f32_dpp v9, v53, v5 quad_perm:[1,1,3,3] row_mask:0xf bank_mask:0xf bound_ctrl:1
	v_mul_f32_dpp v13, v74, v2 quad_perm:[0,0,2,2] row_mask:0xf bank_mask:0xf bound_ctrl:1
	v_add_f32_dpp v10, v10, v10 row_ror:8 row_mask:0xf bank_mask:0xf bound_ctrl:1
	v_mov_b32_e32 v14, v10
	v_fmac_f32_dpp v13, v75, v3 quad_perm:[0,0,2,2] row_mask:0xf bank_mask:0xf bound_ctrl:1
	v_fmac_f32_dpp v13, v74, v4 quad_perm:[1,1,3,3] row_mask:0xf bank_mask:0xf bound_ctrl:1
	v_permlane16_swap_b32 v10, v14
	v_add_f32_e32 v10, v10, v14
	v_fmac_f32_dpp v6, v60, v10 quad_perm:[0,0,2,2] row_mask:0xf bank_mask:0xf bound_ctrl:1
	v_fmac_f32_dpp v7, v61, v10 quad_perm:[0,0,2,2] row_mask:0xf bank_mask:0xf bound_ctrl:1
	v_fmac_f32_dpp v8, v60, v10 quad_perm:[1,1,3,3] row_mask:0xf bank_mask:0xf bound_ctrl:1
	v_fmac_f32_dpp v9, v61, v10 quad_perm:[1,1,3,3] row_mask:0xf bank_mask:0xf bound_ctrl:1
	v_fmac_f32_dpp v13, v75, v5 quad_perm:[1,1,3,3] row_mask:0xf bank_mask:0xf bound_ctrl:1
	ds_write2st64_b32 v30, v12, v13 offset0:12 offset1:13
	ds_read_b64 v[40:41], v35 offset:28672
	ds_read_b64 v[48:49], v35 offset:12288
	ds_read_b64 v[56:57], v35 offset:36864
	ds_read_b64 v[64:65], v35 offset:20480
	ds_read_b64 v[72:73], v35 offset:4096
	ds_read2_b32 v[124:125], v38 offset0:0 offset1:16
	s_waitcnt lgkmcnt(7)
; __device__ __forceinline__ float allreduce16(float x) { x += dppf(x, 0); x += dppf(x, 1); x += dppf(x, 2); x += dppf(x, 3); return x; }
; __device__ void rw_scan(const Params& p, int l, unsigned char* shm, int item) {
;     ...
;                 for (int s2 = 0; s2 < 16; ++s2) {
;                     const int s = hs * 16 + s2, sn = (s + 1) & (TC - 1);
;                     const f32x4 na4 = *(const f32x4*)(sr + 3 * 2048 + sn * 64), nw4 = *(const f32x4*)(sr + 2048 + sn * 64), nb4 = *(const f32x4*)(sr + 4 * 2048 + sn * 64), nk4 = *(const f32x4*)(sr + 2 * 2048 + sn * 64), nr4 = *(const f32x4*)(sr + sn * 64);
;                     const float nvv = sv[sn * 16];
;                     f32x2 tq = S01 * (f32x2){a4[0], a4[1]}; tq = S23 * (f32x2){a4[2], a4[3]} + tq;
;                     const float sav = allreduce16(tq[0] + tq[1]);
;                     f32x2 u0 = (f32x2){b4[0], b4[1]} * sav, u1 = (f32x2){b4[2], b4[3]} * sav;
;                     u0 = (f32x2){k4[0], k4[1]} * vv + u0; u1 = (f32x2){k4[2], k4[3]} * vv + u1;
;                     S01 = S01 * (f32x2){w4[0], w4[1]} + u0; S23 = S23 * (f32x2){w4[2], w4[3]} + u1;
;                     f32x2 oq = S01 * (f32x2){r4[0], r4[1]}; oq = S23 * (f32x2){r4[2], r4[3]} + oq;
;                     pp[s2 * 64] = oq[0] + oq[1];
;                     a4 = na4; w4 = nw4; b4 = nb4; k4 = nk4; r4 = nr4; vv = nvv;
;                 }
;                 { const int s2 = lane >> 2, rr = lane & 3; const float* q_ = part + w * 1024 + s2 * 64 + rr * 16;
;                   const f32x4 x0 = *(const f32x4*)q_, x1 = *(const f32x4*)(q_ + 4), x2 = *(const f32x4*)(q_ + 8), x3 = *(const f32x4*)(q_ + 12);
;                   const float ov = ((x0[0] + x0[1]) + (x0[2] + x0[3])) + ((x1[0] + x1[1]) + (x1[2] + x1[3])) + ((x2[0] + x2[1]) + (x2[2] + x2[3])) + ((x3[0] + x3[1]) + (x3[2] + x3[3]));
;                   const int st2 = ck * TC + hs * 16 + s2; const int t2 = d ? (T - 1 - st2) : st2;
;                   yout[(size_t)(b * T + t2) * 768 + h * 64 + quarter * 16 + w * 4 + rr] = ov; }
	v_mul_f32_dpp v11, v46, v6 quad_perm:[0,0,2,2] row_mask:0xf bank_mask:0xf bound_ctrl:1
	v_mul_f32_dpp v2, v70, v123 quad_perm:[0,0,2,2] row_mask:0xf bank_mask:0xf bound_ctrl:1
	v_fmac_f32_dpp v11, v47, v7 quad_perm:[0,0,2,2] row_mask:0xf bank_mask:0xf bound_ctrl:1
	v_mul_f32_dpp v3, v71, v123 quad_perm:[0,0,2,2] row_mask:0xf bank_mask:0xf bound_ctrl:1
	v_fmac_f32_dpp v11, v46, v8 quad_perm:[1,1,3,3] row_mask:0xf bank_mask:0xf bound_ctrl:1
	v_mul_f32_dpp v4, v70, v123 quad_perm:[1,1,3,3] row_mask:0xf bank_mask:0xf bound_ctrl:1
	v_fmac_f32_dpp v11, v47, v9 quad_perm:[1,1,3,3] row_mask:0xf bank_mask:0xf bound_ctrl:1
	v_mul_f32_dpp v5, v71, v123 quad_perm:[1,1,3,3] row_mask:0xf bank_mask:0xf bound_ctrl:1
	v_fmac_f32_dpp v2, v54, v6 quad_perm:[0,0,2,2] row_mask:0xf bank_mask:0xf bound_ctrl:1
	v_add_f32_dpp v11, v11, v11 quad_perm:[2,3,0,1] row_mask:0xf bank_mask:0xf bound_ctrl:1
	v_fmac_f32_dpp v3, v55, v7 quad_perm:[0,0,2,2] row_mask:0xf bank_mask:0xf bound_ctrl:1
	v_fmac_f32_dpp v4, v54, v8 quad_perm:[1,1,3,3] row_mask:0xf bank_mask:0xf bound_ctrl:1
	v_add_f32_dpp v11, v11, v11 row_ror:4 row_mask:0xf bank_mask:0xf bound_ctrl:1
	v_fmac_f32_dpp v5, v55, v9 quad_perm:[1,1,3,3] row_mask:0xf bank_mask:0xf bound_ctrl:1
	v_mul_f32_dpp v12, v76, v6 quad_perm:[0,0,2,2] row_mask:0xf bank_mask:0xf bound_ctrl:1
	v_add_f32_dpp v11, v11, v11 row_ror:8 row_mask:0xf bank_mask:0xf bound_ctrl:1
	v_mov_b32_e32 v15, v11
	v_fmac_f32_dpp v12, v77, v7 quad_perm:[0,0,2,2] row_mask:0xf bank_mask:0xf bound_ctrl:1
	v_fmac_f32_dpp v12, v76, v8 quad_perm:[1,1,3,3] row_mask:0xf bank_mask:0xf bound_ctrl:1
	v_permlane16_swap_b32 v11, v15
	v_add_f32_e32 v11, v11, v15
	v_fmac_f32_dpp v2, v62, v11 quad_perm:[0,0,2,2] row_mask:0xf bank_mask:0xf bound_ctrl:1
	v_fmac_f32_dpp v3, v63, v11 quad_perm:[0,0,2,2] row_mask:0xf bank_mask:0xf bound_ctrl:1
	v_fmac_f32_dpp v4, v62, v11 quad_perm:[1,1,3,3] row_mask:0xf bank_mask:0xf bound_ctrl:1
	v_fmac_f32_dpp v5, v63, v11 quad_perm:[1,1,3,3] row_mask:0xf bank_mask:0xf bound_ctrl:1
	v_fmac_f32_dpp v12, v77, v9 quad_perm:[1,1,3,3] row_mask:0xf bank_mask:0xf bound_ctrl:1
	ds_read_b64 v[42:43], v35 offset:28928
	ds_read_b64 v[50:51], v35 offset:12544
	ds_read_b64 v[58:59], v35 offset:37120
	ds_read_b64 v[66:67], v35 offset:20736
	ds_read_b64 v[74:75], v35 offset:4352
	s_waitcnt lgkmcnt(5)
	v_mul_f32_dpp v10, v40, v2 quad_perm:[0,0,2,2] row_mask:0xf bank_mask:0xf bound_ctrl:1
	v_mul_f32_dpp v6, v64, v124 quad_perm:[0,0,2,2] row_mask:0xf bank_mask:0xf bound_ctrl:1
	v_fmac_f32_dpp v10, v41, v3 quad_perm:[0,0,2,2] row_mask:0xf bank_mask:0xf bound_ctrl:1
	v_mul_f32_dpp v7, v65, v124 quad_perm:[0,0,2,2] row_mask:0xf bank_mask:0xf bound_ctrl:1
	v_fmac_f32_dpp v10, v40, v4 quad_perm:[1,1,3,3] row_mask:0xf bank_mask:0xf bound_ctrl:1
	v_mul_f32_dpp v8, v64, v124 quad_perm:[1,1,3,3] row_mask:0xf bank_mask:0xf bound_ctrl:1
	v_fmac_f32_dpp v10, v41, v5 quad_perm:[1,1,3,3] row_mask:0xf bank_mask:0xf bound_ctrl:1
	v_mul_f32_dpp v9, v65, v124 quad_perm:[1,1,3,3] row_mask:0xf bank_mask:0xf bound_ctrl:1
	v_fmac_f32_dpp v6, v48, v2 quad_perm:[0,0,2,2] row_mask:0xf bank_mask:0xf bound_ctrl:1
	v_add_f32_dpp v10, v10, v10 quad_perm:[2,3,0,1] row_mask:0xf bank_mask:0xf bound_ctrl:1
	v_fmac_f32_dpp v7, v49, v3 quad_perm:[0,0,2,2] row_mask:0xf bank_mask:0xf bound_ctrl:1
	v_fmac_f32_dpp v8, v48, v4 quad_perm:[1,1,3,3] row_mask:0xf bank_mask:0xf bound_ctrl:1
	v_add_f32_dpp v10, v10, v10 row_ror:4 row_mask:0xf bank_mask:0xf bound_ctrl:1
	v_fmac_f32_dpp v9, v49, v5 quad_perm:[1,1,3,3] row_mask:0xf bank_mask:0xf bound_ctrl:1
	v_mul_f32_dpp v13, v78, v2 quad_perm:[0,0,2,2] row_mask:0xf bank_mask:0xf bound_ctrl:1
	v_add_f32_dpp v10, v10, v10 row_ror:8 row_mask:0xf bank_mask:0xf bound_ctrl:1
	v_mov_b32_e32 v14, v10
	v_fmac_f32_dpp v13, v79, v3 quad_perm:[0,0,2,2] row_mask:0xf bank_mask:0xf bound_ctrl:1
	v_fmac_f32_dpp v13, v78, v4 quad_perm:[1,1,3,3] row_mask:0xf bank_mask:0xf bound_ctrl:1
	v_permlane16_swap_b32 v10, v14
	v_add_f32_e32 v10, v10, v14
	v_fmac_f32_dpp v6, v56, v10 quad_perm:[0,0,2,2] row_mask:0xf bank_mask:0xf bound_ctrl:1
	v_fmac_f32_dpp v7, v57, v10 quad_perm:[0,0,2,2] row_mask:0xf bank_mask:0xf bound_ctrl:1
	v_fmac_f32_dpp v8, v56, v10 quad_perm:[1,1,3,3] row_mask:0xf bank_mask:0xf bound_ctrl:1
	v_fmac_f32_dpp v9, v57, v10 quad_perm:[1,1,3,3] row_mask:0xf bank_mask:0xf bound_ctrl:1
	v_fmac_f32_dpp v13, v79, v5 quad_perm:[1,1,3,3] row_mask:0xf bank_mask:0xf bound_ctrl:1
	ds_write2st64_b32 v30, v12, v13 offset0:14 offset1:15
	ds_read_b128 v[142:145], v34
	ds_read_b128 v[146:149], v34 offset:16
	ds_read_b128 v[150:153], v34 offset:32
	ds_read_b128 v[154:157], v34 offset:48
	ds_read_b64 v[44:45], v35 offset:29184
	ds_read_b64 v[52:53], v35 offset:12800
	ds_read_b64 v[60:61], v35 offset:37376
	ds_read_b64 v[68:69], v35 offset:20992
	ds_read_b64 v[76:77], v35 offset:4608
	ds_read2_b32 v[120:121], v38 offset0:32 offset1:48
	v_add_u32_e32 v182, 16, v23
	v_cndmask_b32_e32 v182, v182, v32, vcc
	v_add_u32_e32 v182, s4, v182
	v_mad_i64_i32 v[180:181], s[6:7], v182, s10, v[24:25]
	s_waitcnt lgkmcnt(9)
	v_add_f32_e32 v158, v142, v143
	v_add_f32_e32 v159, v144, v145
	v_add_f32_e32 v158, v158, v159
	s_waitcnt lgkmcnt(8)
	v_add_f32_e32 v159, v146, v147
	v_add_f32_e32 v179, v148, v149
	v_add_f32_e32 v159, v159, v179
	v_add_f32_e32 v158, v158, v159
	s_waitcnt lgkmcnt(7)
	v_add_f32_e32 v159, v150, v151
	v_add_f32_e32 v179, v152, v153
	v_add_f32_e32 v159, v159, v179
	v_add_f32_e32 v158, v158, v159
	s_waitcnt lgkmcnt(6)
	v_add_f32_e32 v159, v154, v155
	v_add_f32_e32 v179, v156, v157
	v_add_f32_e32 v159, v159, v179
	v_add_f32_e32 v158, v158, v159
	global_store_dword v[180:181], v158, off
	s_waitcnt lgkmcnt(11)
; __device__ __forceinline__ float allreduce16(float x) { x += dppf(x, 0); x += dppf(x, 1); x += dppf(x, 2); x += dppf(x, 3); return x; }
; __device__ void rw_scan(const Params& p, int l, unsigned char* shm, int item) {
;     ...
;                 for (int s2 = 0; s2 < 16; ++s2) {
;                     const int s = hs * 16 + s2, sn = (s + 1) & (TC - 1);
;                     const f32x4 na4 = *(const f32x4*)(sr + 3 * 2048 + sn * 64), nw4 = *(const f32x4*)(sr + 2048 + sn * 64), nb4 = *(const f32x4*)(sr + 4 * 2048 + sn * 64), nk4 = *(const f32x4*)(sr + 2 * 2048 + sn * 64), nr4 = *(const f32x4*)(sr + sn * 64);
;                     const float nvv = sv[sn * 16];
;                     f32x2 tq = S01 * (f32x2){a4[0], a4[1]}; tq = S23 * (f32x2){a4[2], a4[3]} + tq;
;                     const float sav = allreduce16(tq[0] + tq[1]);
;                     f32x2 u0 = (f32x2){b4[0], b4[1]} * sav, u1 = (f32x2){b4[2], b4[3]} * sav;
;                     u0 = (f32x2){k4[0], k4[1]} * vv + u0; u1 = (f32x2){k4[2], k4[3]} * vv + u1;
;                     S01 = S01 * (f32x2){w4[0], w4[1]} + u0; S23 = S23 * (f32x2){w4[2], w4[3]} + u1;
;                     f32x2 oq = S01 * (f32x2){r4[0], r4[1]}; oq = S23 * (f32x2){r4[2], r4[3]} + oq;
;                     pp[s2 * 64] = oq[0] + oq[1];
;                     a4 = na4; w4 = nw4; b4 = nb4; k4 = nk4; r4 = nr4; vv = nvv;
	v_mul_f32_dpp v11, v42, v6 quad_perm:[0,0,2,2] row_mask:0xf bank_mask:0xf bound_ctrl:1
	v_mul_f32_dpp v2, v66, v125 quad_perm:[0,0,2,2] row_mask:0xf bank_mask:0xf bound_ctrl:1
	v_fmac_f32_dpp v11, v43, v7 quad_perm:[0,0,2,2] row_mask:0xf bank_mask:0xf bound_ctrl:1
	v_mul_f32_dpp v3, v67, v125 quad_perm:[0,0,2,2] row_mask:0xf bank_mask:0xf bound_ctrl:1
	v_fmac_f32_dpp v11, v42, v8 quad_perm:[1,1,3,3] row_mask:0xf bank_mask:0xf bound_ctrl:1
	v_mul_f32_dpp v4, v66, v125 quad_perm:[1,1,3,3] row_mask:0xf bank_mask:0xf bound_ctrl:1
	v_fmac_f32_dpp v11, v43, v9 quad_perm:[1,1,3,3] row_mask:0xf bank_mask:0xf bound_ctrl:1
	v_mul_f32_dpp v5, v67, v125 quad_perm:[1,1,3,3] row_mask:0xf bank_mask:0xf bound_ctrl:1
	v_fmac_f32_dpp v2, v50, v6 quad_perm:[0,0,2,2] row_mask:0xf bank_mask:0xf bound_ctrl:1
	v_add_f32_dpp v11, v11, v11 quad_perm:[2,3,0,1] row_mask:0xf bank_mask:0xf bound_ctrl:1
	v_fmac_f32_dpp v3, v51, v7 quad_perm:[0,0,2,2] row_mask:0xf bank_mask:0xf bound_ctrl:1
	v_fmac_f32_dpp v4, v50, v8 quad_perm:[1,1,3,3] row_mask:0xf bank_mask:0xf bound_ctrl:1
	v_add_f32_dpp v11, v11, v11 row_ror:4 row_mask:0xf bank_mask:0xf bound_ctrl:1
	v_fmac_f32_dpp v5, v51, v9 quad_perm:[1,1,3,3] row_mask:0xf bank_mask:0xf bound_ctrl:1
	v_mul_f32_dpp v12, v72, v6 quad_perm:[0,0,2,2] row_mask:0xf bank_mask:0xf bound_ctrl:1
	v_add_f32_dpp v11, v11, v11 row_ror:8 row_mask:0xf bank_mask:0xf bound_ctrl:1
	v_mov_b32_e32 v15, v11
	v_fmac_f32_dpp v12, v73, v7 quad_perm:[0,0,2,2] row_mask:0xf bank_mask:0xf bound_ctrl:1
	v_fmac_f32_dpp v12, v72, v8 quad_perm:[1,1,3,3] row_mask:0xf bank_mask:0xf bound_ctrl:1
	v_permlane16_swap_b32 v11, v15
	v_add_f32_e32 v11, v11, v15
	v_fmac_f32_dpp v2, v58, v11 quad_perm:[0,0,2,2] row_mask:0xf bank_mask:0xf bound_ctrl:1
	v_fmac_f32_dpp v3, v59, v11 quad_perm:[0,0,2,2] row_mask:0xf bank_mask:0xf bound_ctrl:1
	v_fmac_f32_dpp v4, v58, v11 quad_perm:[1,1,3,3] row_mask:0xf bank_mask:0xf bound_ctrl:1
	v_fmac_f32_dpp v5, v59, v11 quad_perm:[1,1,3,3] row_mask:0xf bank_mask:0xf bound_ctrl:1
	v_fmac_f32_dpp v12, v73, v9 quad_perm:[1,1,3,3] row_mask:0xf bank_mask:0xf bound_ctrl:1
	ds_read_b64 v[46:47], v35 offset:29440
	ds_read_b64 v[54:55], v35 offset:13056
	ds_read_b64 v[62:63], v35 offset:37632
	ds_read_b64 v[70:71], v35 offset:21248
	ds_read_b64 v[78:79], v35 offset:4864
	s_waitcnt lgkmcnt(5)
	v_mul_f32_dpp v10, v44, v2 quad_perm:[0,0,2,2] row_mask:0xf bank_mask:0xf bound_ctrl:1
	v_mul_f32_dpp v6, v68, v120 quad_perm:[0,0,2,2] row_mask:0xf bank_mask:0xf bound_ctrl:1
	v_fmac_f32_dpp v10, v45, v3 quad_perm:[0,0,2,2] row_mask:0xf bank_mask:0xf bound_ctrl:1
	v_mul_f32_dpp v7, v69, v120 quad_perm:[0,0,2,2] row_mask:0xf bank_mask:0xf bound_ctrl:1
	v_fmac_f32_dpp v10, v44, v4 quad_perm:[1,1,3,3] row_mask:0xf bank_mask:0xf bound_ctrl:1
	v_mul_f32_dpp v8, v68, v120 quad_perm:[1,1,3,3] row_mask:0xf bank_mask:0xf bound_ctrl:1
	v_fmac_f32_dpp v10, v45, v5 quad_perm:[1,1,3,3] row_mask:0xf bank_mask:0xf bound_ctrl:1
	v_mul_f32_dpp v9, v69, v120 quad_perm:[1,1,3,3] row_mask:0xf bank_mask:0xf bound_ctrl:1
	v_fmac_f32_dpp v6, v52, v2 quad_perm:[0,0,2,2] row_mask:0xf bank_mask:0xf bound_ctrl:1
	v_add_f32_dpp v10, v10, v10 quad_perm:[2,3,0,1] row_mask:0xf bank_mask:0xf bound_ctrl:1
	v_fmac_f32_dpp v7, v53, v3 quad_perm:[0,0,2,2] row_mask:0xf bank_mask:0xf bound_ctrl:1
	v_fmac_f32_dpp v8, v52, v4 quad_perm:[1,1,3,3] row_mask:0xf bank_mask:0xf bound_ctrl:1
	v_add_f32_dpp v10, v10, v10 row_ror:4 row_mask:0xf bank_mask:0xf bound_ctrl:1
	v_fmac_f32_dpp v9, v53, v5 quad_perm:[1,1,3,3] row_mask:0xf bank_mask:0xf bound_ctrl:1
	v_mul_f32_dpp v13, v74, v2 quad_perm:[0,0,2,2] row_mask:0xf bank_mask:0xf bound_ctrl:1
	v_add_f32_dpp v10, v10, v10 row_ror:8 row_mask:0xf bank_mask:0xf bound_ctrl:1
	v_mov_b32_e32 v14, v10
	v_fmac_f32_dpp v13, v75, v3 quad_perm:[0,0,2,2] row_mask:0xf bank_mask:0xf bound_ctrl:1
	v_fmac_f32_dpp v13, v74, v4 quad_perm:[1,1,3,3] row_mask:0xf bank_mask:0xf bound_ctrl:1
	v_permlane16_swap_b32 v10, v14
	v_add_f32_e32 v10, v10, v14
	v_fmac_f32_dpp v6, v60, v10 quad_perm:[0,0,2,2] row_mask:0xf bank_mask:0xf bound_ctrl:1
	v_fmac_f32_dpp v7, v61, v10 quad_perm:[0,0,2,2] row_mask:0xf bank_mask:0xf bound_ctrl:1
	v_fmac_f32_dpp v8, v60, v10 quad_perm:[1,1,3,3] row_mask:0xf bank_mask:0xf bound_ctrl:1
	v_fmac_f32_dpp v9, v61, v10 quad_perm:[1,1,3,3] row_mask:0xf bank_mask:0xf bound_ctrl:1
	v_fmac_f32_dpp v13, v75, v5 quad_perm:[1,1,3,3] row_mask:0xf bank_mask:0xf bound_ctrl:1
	ds_write2st64_b32 v30, v12, v13 offset0:0 offset1:1
	ds_read_b64 v[40:41], v35 offset:29696
	ds_read_b64 v[48:49], v35 offset:13312
	ds_read_b64 v[56:57], v35 offset:37888
	ds_read_b64 v[64:65], v35 offset:21504
	ds_read_b64 v[72:73], v35 offset:5120
	ds_read2_b32 v[122:123], v38 offset0:64 offset1:80
	s_waitcnt lgkmcnt(7)
; __device__ __forceinline__ float allreduce16(float x) { x += dppf(x, 0); x += dppf(x, 1); x += dppf(x, 2); x += dppf(x, 3); return x; }
; __device__ void rw_scan(const Params& p, int l, unsigned char* shm, int item) {
;     ...
;                 for (int s2 = 0; s2 < 16; ++s2) {
;                     const int s = hs * 16 + s2, sn = (s + 1) & (TC - 1);
;                     const f32x4 na4 = *(const f32x4*)(sr + 3 * 2048 + sn * 64), nw4 = *(const f32x4*)(sr + 2048 + sn * 64), nb4 = *(const f32x4*)(sr + 4 * 2048 + sn * 64), nk4 = *(const f32x4*)(sr + 2 * 2048 + sn * 64), nr4 = *(const f32x4*)(sr + sn * 64);
;                     const float nvv = sv[sn * 16];
;                     f32x2 tq = S01 * (f32x2){a4[0], a4[1]}; tq = S23 * (f32x2){a4[2], a4[3]} + tq;
;                     const float sav = allreduce16(tq[0] + tq[1]);
;                     f32x2 u0 = (f32x2){b4[0], b4[1]} * sav, u1 = (f32x2){b4[2], b4[3]} * sav;
;                     u0 = (f32x2){k4[0], k4[1]} * vv + u0; u1 = (f32x2){k4[2], k4[3]} * vv + u1;
;                     S01 = S01 * (f32x2){w4[0], w4[1]} + u0; S23 = S23 * (f32x2){w4[2], w4[3]} + u1;
;                     f32x2 oq = S01 * (f32x2){r4[0], r4[1]}; oq = S23 * (f32x2){r4[2], r4[3]} + oq;
;                     pp[s2 * 64] = oq[0] + oq[1];
;                     a4 = na4; w4 = nw4; b4 = nb4; k4 = nk4; r4 = nr4; vv = nvv;
	v_mul_f32_dpp v11, v46, v6 quad_perm:[0,0,2,2] row_mask:0xf bank_mask:0xf bound_ctrl:1
	v_mul_f32_dpp v2, v70, v121 quad_perm:[0,0,2,2] row_mask:0xf bank_mask:0xf bound_ctrl:1
	v_fmac_f32_dpp v11, v47, v7 quad_perm:[0,0,2,2] row_mask:0xf bank_mask:0xf bound_ctrl:1
	v_mul_f32_dpp v3, v71, v121 quad_perm:[0,0,2,2] row_mask:0xf bank_mask:0xf bound_ctrl:1
	v_fmac_f32_dpp v11, v46, v8 quad_perm:[1,1,3,3] row_mask:0xf bank_mask:0xf bound_ctrl:1
	v_mul_f32_dpp v4, v70, v121 quad_perm:[1,1,3,3] row_mask:0xf bank_mask:0xf bound_ctrl:1
	v_fmac_f32_dpp v11, v47, v9 quad_perm:[1,1,3,3] row_mask:0xf bank_mask:0xf bound_ctrl:1
	v_mul_f32_dpp v5, v71, v121 quad_perm:[1,1,3,3] row_mask:0xf bank_mask:0xf bound_ctrl:1
	v_fmac_f32_dpp v2, v54, v6 quad_perm:[0,0,2,2] row_mask:0xf bank_mask:0xf bound_ctrl:1
	v_add_f32_dpp v11, v11, v11 quad_perm:[2,3,0,1] row_mask:0xf bank_mask:0xf bound_ctrl:1
	v_fmac_f32_dpp v3, v55, v7 quad_perm:[0,0,2,2] row_mask:0xf bank_mask:0xf bound_ctrl:1
	v_fmac_f32_dpp v4, v54, v8 quad_perm:[1,1,3,3] row_mask:0xf bank_mask:0xf bound_ctrl:1
	v_add_f32_dpp v11, v11, v11 row_ror:4 row_mask:0xf bank_mask:0xf bound_ctrl:1
	v_fmac_f32_dpp v5, v55, v9 quad_perm:[1,1,3,3] row_mask:0xf bank_mask:0xf bound_ctrl:1
	v_mul_f32_dpp v12, v76, v6 quad_perm:[0,0,2,2] row_mask:0xf bank_mask:0xf bound_ctrl:1
	v_add_f32_dpp v11, v11, v11 row_ror:8 row_mask:0xf bank_mask:0xf bound_ctrl:1
	v_mov_b32_e32 v15, v11
	v_fmac_f32_dpp v12, v77, v7 quad_perm:[0,0,2,2] row_mask:0xf bank_mask:0xf bound_ctrl:1
	v_fmac_f32_dpp v12, v76, v8 quad_perm:[1,1,3,3] row_mask:0xf bank_mask:0xf bound_ctrl:1
	v_permlane16_swap_b32 v11, v15
	v_add_f32_e32 v11, v11, v15
	v_fmac_f32_dpp v2, v62, v11 quad_perm:[0,0,2,2] row_mask:0xf bank_mask:0xf bound_ctrl:1
	v_fmac_f32_dpp v3, v63, v11 quad_perm:[0,0,2,2] row_mask:0xf bank_mask:0xf bound_ctrl:1
	v_fmac_f32_dpp v4, v62, v11 quad_perm:[1,1,3,3] row_mask:0xf bank_mask:0xf bound_ctrl:1
	v_fmac_f32_dpp v5, v63, v11 quad_perm:[1,1,3,3] row_mask:0xf bank_mask:0xf bound_ctrl:1
	v_fmac_f32_dpp v12, v77, v9 quad_perm:[1,1,3,3] row_mask:0xf bank_mask:0xf bound_ctrl:1
	ds_read_b64 v[42:43], v35 offset:29952
	ds_read_b64 v[50:51], v35 offset:13568
	ds_read_b64 v[58:59], v35 offset:38144
	ds_read_b64 v[66:67], v35 offset:21760
	ds_read_b64 v[74:75], v35 offset:5376
	s_waitcnt lgkmcnt(5)
	v_mul_f32_dpp v10, v40, v2 quad_perm:[0,0,2,2] row_mask:0xf bank_mask:0xf bound_ctrl:1
	v_mul_f32_dpp v6, v64, v122 quad_perm:[0,0,2,2] row_mask:0xf bank_mask:0xf bound_ctrl:1
	v_fmac_f32_dpp v10, v41, v3 quad_perm:[0,0,2,2] row_mask:0xf bank_mask:0xf bound_ctrl:1
	v_mul_f32_dpp v7, v65, v122 quad_perm:[0,0,2,2] row_mask:0xf bank_mask:0xf bound_ctrl:1
	v_fmac_f32_dpp v10, v40, v4 quad_perm:[1,1,3,3] row_mask:0xf bank_mask:0xf bound_ctrl:1
	v_mul_f32_dpp v8, v64, v122 quad_perm:[1,1,3,3] row_mask:0xf bank_mask:0xf bound_ctrl:1
	v_fmac_f32_dpp v10, v41, v5 quad_perm:[1,1,3,3] row_mask:0xf bank_mask:0xf bound_ctrl:1
	v_mul_f32_dpp v9, v65, v122 quad_perm:[1,1,3,3] row_mask:0xf bank_mask:0xf bound_ctrl:1
	v_fmac_f32_dpp v6, v48, v2 quad_perm:[0,0,2,2] row_mask:0xf bank_mask:0xf bound_ctrl:1
	v_add_f32_dpp v10, v10, v10 quad_perm:[2,3,0,1] row_mask:0xf bank_mask:0xf bound_ctrl:1
	v_fmac_f32_dpp v7, v49, v3 quad_perm:[0,0,2,2] row_mask:0xf bank_mask:0xf bound_ctrl:1
	v_fmac_f32_dpp v8, v48, v4 quad_perm:[1,1,3,3] row_mask:0xf bank_mask:0xf bound_ctrl:1
	v_add_f32_dpp v10, v10, v10 row_ror:4 row_mask:0xf bank_mask:0xf bound_ctrl:1
	v_fmac_f32_dpp v9, v49, v5 quad_perm:[1,1,3,3] row_mask:0xf bank_mask:0xf bound_ctrl:1
	v_mul_f32_dpp v13, v78, v2 quad_perm:[0,0,2,2] row_mask:0xf bank_mask:0xf bound_ctrl:1
	v_add_f32_dpp v10, v10, v10 row_ror:8 row_mask:0xf bank_mask:0xf bound_ctrl:1
	v_mov_b32_e32 v14, v10
	v_fmac_f32_dpp v13, v79, v3 quad_perm:[0,0,2,2] row_mask:0xf bank_mask:0xf bound_ctrl:1
	v_fmac_f32_dpp v13, v78, v4 quad_perm:[1,1,3,3] row_mask:0xf bank_mask:0xf bound_ctrl:1
	v_permlane16_swap_b32 v10, v14
	v_add_f32_e32 v10, v10, v14
	v_fmac_f32_dpp v6, v56, v10 quad_perm:[0,0,2,2] row_mask:0xf bank_mask:0xf bound_ctrl:1
	v_fmac_f32_dpp v7, v57, v10 quad_perm:[0,0,2,2] row_mask:0xf bank_mask:0xf bound_ctrl:1
	v_fmac_f32_dpp v8, v56, v10 quad_perm:[1,1,3,3] row_mask:0xf bank_mask:0xf bound_ctrl:1
	v_fmac_f32_dpp v9, v57, v10 quad_perm:[1,1,3,3] row_mask:0xf bank_mask:0xf bound_ctrl:1
	v_fmac_f32_dpp v13, v79, v5 quad_perm:[1,1,3,3] row_mask:0xf bank_mask:0xf bound_ctrl:1
	ds_write2st64_b32 v30, v12, v13 offset0:2 offset1:3
	ds_read_b64 v[44:45], v35 offset:30208
	ds_read_b64 v[52:53], v35 offset:13824
	ds_read_b64 v[60:61], v35 offset:38400
	ds_read_b64 v[68:69], v35 offset:22016
	ds_read_b64 v[76:77], v35 offset:5632
	ds_read2_b32 v[124:125], v38 offset0:96 offset1:112
	s_waitcnt lgkmcnt(7)
; __device__ __forceinline__ float allreduce16(float x) { x += dppf(x, 0); x += dppf(x, 1); x += dppf(x, 2); x += dppf(x, 3); return x; }
; __device__ void rw_scan(const Params& p, int l, unsigned char* shm, int item) {
;     ...
;                 for (int s2 = 0; s2 < 16; ++s2) {
;                     const int s = hs * 16 + s2, sn = (s + 1) & (TC - 1);
;                     const f32x4 na4 = *(const f32x4*)(sr + 3 * 2048 + sn * 64), nw4 = *(const f32x4*)(sr + 2048 + sn * 64), nb4 = *(const f32x4*)(sr + 4 * 2048 + sn * 64), nk4 = *(const f32x4*)(sr + 2 * 2048 + sn * 64), nr4 = *(const f32x4*)(sr + sn * 64);
;                     const float nvv = sv[sn * 16];
;                     f32x2 tq = S01 * (f32x2){a4[0], a4[1]}; tq = S23 * (f32x2){a4[2], a4[3]} + tq;
;                     const float sav = allreduce16(tq[0] + tq[1]);
;                     f32x2 u0 = (f32x2){b4[0], b4[1]} * sav, u1 = (f32x2){b4[2], b4[3]} * sav;
;                     u0 = (f32x2){k4[0], k4[1]} * vv + u0; u1 = (f32x2){k4[2], k4[3]} * vv + u1;
;                     S01 = S01 * (f32x2){w4[0], w4[1]} + u0; S23 = S23 * (f32x2){w4[2], w4[3]} + u1;
;                     f32x2 oq = S01 * (f32x2){r4[0], r4[1]}; oq = S23 * (f32x2){r4[2], r4[3]} + oq;
;                     pp[s2 * 64] = oq[0] + oq[1];
;                     a4 = na4; w4 = nw4; b4 = nb4; k4 = nk4; r4 = nr4; vv = nvv;
	v_mul_f32_dpp v11, v42, v6 quad_perm:[0,0,2,2] row_mask:0xf bank_mask:0xf bound_ctrl:1
	v_mul_f32_dpp v2, v66, v123 quad_perm:[0,0,2,2] row_mask:0xf bank_mask:0xf bound_ctrl:1
	v_fmac_f32_dpp v11, v43, v7 quad_perm:[0,0,2,2] row_mask:0xf bank_mask:0xf bound_ctrl:1
	v_mul_f32_dpp v3, v67, v123 quad_perm:[0,0,2,2] row_mask:0xf bank_mask:0xf bound_ctrl:1
	v_fmac_f32_dpp v11, v42, v8 quad_perm:[1,1,3,3] row_mask:0xf bank_mask:0xf bound_ctrl:1
	v_mul_f32_dpp v4, v66, v123 quad_perm:[1,1,3,3] row_mask:0xf bank_mask:0xf bound_ctrl:1
	v_fmac_f32_dpp v11, v43, v9 quad_perm:[1,1,3,3] row_mask:0xf bank_mask:0xf bound_ctrl:1
	v_mul_f32_dpp v5, v67, v123 quad_perm:[1,1,3,3] row_mask:0xf bank_mask:0xf bound_ctrl:1
	v_fmac_f32_dpp v2, v50, v6 quad_perm:[0,0,2,2] row_mask:0xf bank_mask:0xf bound_ctrl:1
	v_add_f32_dpp v11, v11, v11 quad_perm:[2,3,0,1] row_mask:0xf bank_mask:0xf bound_ctrl:1
	v_fmac_f32_dpp v3, v51, v7 quad_perm:[0,0,2,2] row_mask:0xf bank_mask:0xf bound_ctrl:1
	v_fmac_f32_dpp v4, v50, v8 quad_perm:[1,1,3,3] row_mask:0xf bank_mask:0xf bound_ctrl:1
	v_add_f32_dpp v11, v11, v11 row_ror:4 row_mask:0xf bank_mask:0xf bound_ctrl:1
	v_fmac_f32_dpp v5, v51, v9 quad_perm:[1,1,3,3] row_mask:0xf bank_mask:0xf bound_ctrl:1
	v_mul_f32_dpp v12, v72, v6 quad_perm:[0,0,2,2] row_mask:0xf bank_mask:0xf bound_ctrl:1
	v_add_f32_dpp v11, v11, v11 row_ror:8 row_mask:0xf bank_mask:0xf bound_ctrl:1
	v_mov_b32_e32 v15, v11
	v_fmac_f32_dpp v12, v73, v7 quad_perm:[0,0,2,2] row_mask:0xf bank_mask:0xf bound_ctrl:1
	v_fmac_f32_dpp v12, v72, v8 quad_perm:[1,1,3,3] row_mask:0xf bank_mask:0xf bound_ctrl:1
	v_permlane16_swap_b32 v11, v15
	v_add_f32_e32 v11, v11, v15
	v_fmac_f32_dpp v2, v58, v11 quad_perm:[0,0,2,2] row_mask:0xf bank_mask:0xf bound_ctrl:1
	v_fmac_f32_dpp v3, v59, v11 quad_perm:[0,0,2,2] row_mask:0xf bank_mask:0xf bound_ctrl:1
	v_fmac_f32_dpp v4, v58, v11 quad_perm:[1,1,3,3] row_mask:0xf bank_mask:0xf bound_ctrl:1
	v_fmac_f32_dpp v5, v59, v11 quad_perm:[1,1,3,3] row_mask:0xf bank_mask:0xf bound_ctrl:1
	v_fmac_f32_dpp v12, v73, v9 quad_perm:[1,1,3,3] row_mask:0xf bank_mask:0xf bound_ctrl:1
	ds_read_b64 v[46:47], v35 offset:30464
	ds_read_b64 v[54:55], v35 offset:14080
	ds_read_b64 v[62:63], v35 offset:38656
	ds_read_b64 v[70:71], v35 offset:22272
	ds_read_b64 v[78:79], v35 offset:5888
	s_waitcnt lgkmcnt(5)
	v_mul_f32_dpp v10, v44, v2 quad_perm:[0,0,2,2] row_mask:0xf bank_mask:0xf bound_ctrl:1
	v_mul_f32_dpp v6, v68, v124 quad_perm:[0,0,2,2] row_mask:0xf bank_mask:0xf bound_ctrl:1
	v_fmac_f32_dpp v10, v45, v3 quad_perm:[0,0,2,2] row_mask:0xf bank_mask:0xf bound_ctrl:1
	v_mul_f32_dpp v7, v69, v124 quad_perm:[0,0,2,2] row_mask:0xf bank_mask:0xf bound_ctrl:1
	v_fmac_f32_dpp v10, v44, v4 quad_perm:[1,1,3,3] row_mask:0xf bank_mask:0xf bound_ctrl:1
	v_mul_f32_dpp v8, v68, v124 quad_perm:[1,1,3,3] row_mask:0xf bank_mask:0xf bound_ctrl:1
	v_fmac_f32_dpp v10, v45, v5 quad_perm:[1,1,3,3] row_mask:0xf bank_mask:0xf bound_ctrl:1
	v_mul_f32_dpp v9, v69, v124 quad_perm:[1,1,3,3] row_mask:0xf bank_mask:0xf bound_ctrl:1
	v_fmac_f32_dpp v6, v52, v2 quad_perm:[0,0,2,2] row_mask:0xf bank_mask:0xf bound_ctrl:1
	v_add_f32_dpp v10, v10, v10 quad_perm:[2,3,0,1] row_mask:0xf bank_mask:0xf bound_ctrl:1
	v_fmac_f32_dpp v7, v53, v3 quad_perm:[0,0,2,2] row_mask:0xf bank_mask:0xf bound_ctrl:1
	v_fmac_f32_dpp v8, v52, v4 quad_perm:[1,1,3,3] row_mask:0xf bank_mask:0xf bound_ctrl:1
	v_add_f32_dpp v10, v10, v10 row_ror:4 row_mask:0xf bank_mask:0xf bound_ctrl:1
	v_fmac_f32_dpp v9, v53, v5 quad_perm:[1,1,3,3] row_mask:0xf bank_mask:0xf bound_ctrl:1
	v_mul_f32_dpp v13, v74, v2 quad_perm:[0,0,2,2] row_mask:0xf bank_mask:0xf bound_ctrl:1
	v_add_f32_dpp v10, v10, v10 row_ror:8 row_mask:0xf bank_mask:0xf bound_ctrl:1
	v_mov_b32_e32 v14, v10
	v_fmac_f32_dpp v13, v75, v3 quad_perm:[0,0,2,2] row_mask:0xf bank_mask:0xf bound_ctrl:1
	v_fmac_f32_dpp v13, v74, v4 quad_perm:[1,1,3,3] row_mask:0xf bank_mask:0xf bound_ctrl:1
	v_permlane16_swap_b32 v10, v14
	v_add_f32_e32 v10, v10, v14
	v_fmac_f32_dpp v6, v60, v10 quad_perm:[0,0,2,2] row_mask:0xf bank_mask:0xf bound_ctrl:1
	v_fmac_f32_dpp v7, v61, v10 quad_perm:[0,0,2,2] row_mask:0xf bank_mask:0xf bound_ctrl:1
	v_fmac_f32_dpp v8, v60, v10 quad_perm:[1,1,3,3] row_mask:0xf bank_mask:0xf bound_ctrl:1
	v_fmac_f32_dpp v9, v61, v10 quad_perm:[1,1,3,3] row_mask:0xf bank_mask:0xf bound_ctrl:1
	v_fmac_f32_dpp v13, v75, v5 quad_perm:[1,1,3,3] row_mask:0xf bank_mask:0xf bound_ctrl:1
	ds_write2st64_b32 v30, v12, v13 offset0:4 offset1:5
	ds_read_b64 v[40:41], v35 offset:30720
	ds_read_b64 v[48:49], v35 offset:14336
	ds_read_b64 v[56:57], v35 offset:38912
	ds_read_b64 v[64:65], v35 offset:22528
	ds_read_b64 v[72:73], v35 offset:6144
	ds_read2_b32 v[120:121], v38 offset0:128 offset1:144
	s_waitcnt lgkmcnt(7)
; __device__ __forceinline__ float allreduce16(float x) { x += dppf(x, 0); x += dppf(x, 1); x += dppf(x, 2); x += dppf(x, 3); return x; }
; __device__ void rw_scan(const Params& p, int l, unsigned char* shm, int item) {
;     ...
;                 for (int s2 = 0; s2 < 16; ++s2) {
;                     const int s = hs * 16 + s2, sn = (s + 1) & (TC - 1);
;                     const f32x4 na4 = *(const f32x4*)(sr + 3 * 2048 + sn * 64), nw4 = *(const f32x4*)(sr + 2048 + sn * 64), nb4 = *(const f32x4*)(sr + 4 * 2048 + sn * 64), nk4 = *(const f32x4*)(sr + 2 * 2048 + sn * 64), nr4 = *(const f32x4*)(sr + sn * 64);
;                     const float nvv = sv[sn * 16];
;                     f32x2 tq = S01 * (f32x2){a4[0], a4[1]}; tq = S23 * (f32x2){a4[2], a4[3]} + tq;
;                     const float sav = allreduce16(tq[0] + tq[1]);
;                     f32x2 u0 = (f32x2){b4[0], b4[1]} * sav, u1 = (f32x2){b4[2], b4[3]} * sav;
;                     u0 = (f32x2){k4[0], k4[1]} * vv + u0; u1 = (f32x2){k4[2], k4[3]} * vv + u1;
;                     S01 = S01 * (f32x2){w4[0], w4[1]} + u0; S23 = S23 * (f32x2){w4[2], w4[3]} + u1;
;                     f32x2 oq = S01 * (f32x2){r4[0], r4[1]}; oq = S23 * (f32x2){r4[2], r4[3]} + oq;
;                     pp[s2 * 64] = oq[0] + oq[1];
;                     a4 = na4; w4 = nw4; b4 = nb4; k4 = nk4; r4 = nr4; vv = nvv;
	v_mul_f32_dpp v11, v46, v6 quad_perm:[0,0,2,2] row_mask:0xf bank_mask:0xf bound_ctrl:1
	v_mul_f32_dpp v2, v70, v125 quad_perm:[0,0,2,2] row_mask:0xf bank_mask:0xf bound_ctrl:1
	v_fmac_f32_dpp v11, v47, v7 quad_perm:[0,0,2,2] row_mask:0xf bank_mask:0xf bound_ctrl:1
	v_mul_f32_dpp v3, v71, v125 quad_perm:[0,0,2,2] row_mask:0xf bank_mask:0xf bound_ctrl:1
	v_fmac_f32_dpp v11, v46, v8 quad_perm:[1,1,3,3] row_mask:0xf bank_mask:0xf bound_ctrl:1
	v_mul_f32_dpp v4, v70, v125 quad_perm:[1,1,3,3] row_mask:0xf bank_mask:0xf bound_ctrl:1
	v_fmac_f32_dpp v11, v47, v9 quad_perm:[1,1,3,3] row_mask:0xf bank_mask:0xf bound_ctrl:1
	v_mul_f32_dpp v5, v71, v125 quad_perm:[1,1,3,3] row_mask:0xf bank_mask:0xf bound_ctrl:1
	v_fmac_f32_dpp v2, v54, v6 quad_perm:[0,0,2,2] row_mask:0xf bank_mask:0xf bound_ctrl:1
	v_add_f32_dpp v11, v11, v11 quad_perm:[2,3,0,1] row_mask:0xf bank_mask:0xf bound_ctrl:1
	v_fmac_f32_dpp v3, v55, v7 quad_perm:[0,0,2,2] row_mask:0xf bank_mask:0xf bound_ctrl:1
	v_fmac_f32_dpp v4, v54, v8 quad_perm:[1,1,3,3] row_mask:0xf bank_mask:0xf bound_ctrl:1
	v_add_f32_dpp v11, v11, v11 row_ror:4 row_mask:0xf bank_mask:0xf bound_ctrl:1
	v_fmac_f32_dpp v5, v55, v9 quad_perm:[1,1,3,3] row_mask:0xf bank_mask:0xf bound_ctrl:1
	v_mul_f32_dpp v12, v76, v6 quad_perm:[0,0,2,2] row_mask:0xf bank_mask:0xf bound_ctrl:1
	v_add_f32_dpp v11, v11, v11 row_ror:8 row_mask:0xf bank_mask:0xf bound_ctrl:1
	v_mov_b32_e32 v15, v11
	v_fmac_f32_dpp v12, v77, v7 quad_perm:[0,0,2,2] row_mask:0xf bank_mask:0xf bound_ctrl:1
	v_fmac_f32_dpp v12, v76, v8 quad_perm:[1,1,3,3] row_mask:0xf bank_mask:0xf bound_ctrl:1
	v_permlane16_swap_b32 v11, v15
	v_add_f32_e32 v11, v11, v15
	v_fmac_f32_dpp v2, v62, v11 quad_perm:[0,0,2,2] row_mask:0xf bank_mask:0xf bound_ctrl:1
	v_fmac_f32_dpp v3, v63, v11 quad_perm:[0,0,2,2] row_mask:0xf bank_mask:0xf bound_ctrl:1
	v_fmac_f32_dpp v4, v62, v11 quad_perm:[1,1,3,3] row_mask:0xf bank_mask:0xf bound_ctrl:1
	v_fmac_f32_dpp v5, v63, v11 quad_perm:[1,1,3,3] row_mask:0xf bank_mask:0xf bound_ctrl:1
	v_fmac_f32_dpp v12, v77, v9 quad_perm:[1,1,3,3] row_mask:0xf bank_mask:0xf bound_ctrl:1
	ds_read_b64 v[42:43], v35 offset:30976
	ds_read_b64 v[50:51], v35 offset:14592
	ds_read_b64 v[58:59], v35 offset:39168
	ds_read_b64 v[66:67], v35 offset:22784
	ds_read_b64 v[74:75], v35 offset:6400
	s_waitcnt lgkmcnt(5)
	v_mul_f32_dpp v10, v40, v2 quad_perm:[0,0,2,2] row_mask:0xf bank_mask:0xf bound_ctrl:1
	v_mul_f32_dpp v6, v64, v120 quad_perm:[0,0,2,2] row_mask:0xf bank_mask:0xf bound_ctrl:1
	v_fmac_f32_dpp v10, v41, v3 quad_perm:[0,0,2,2] row_mask:0xf bank_mask:0xf bound_ctrl:1
	v_mul_f32_dpp v7, v65, v120 quad_perm:[0,0,2,2] row_mask:0xf bank_mask:0xf bound_ctrl:1
	v_fmac_f32_dpp v10, v40, v4 quad_perm:[1,1,3,3] row_mask:0xf bank_mask:0xf bound_ctrl:1
	v_mul_f32_dpp v8, v64, v120 quad_perm:[1,1,3,3] row_mask:0xf bank_mask:0xf bound_ctrl:1
	v_fmac_f32_dpp v10, v41, v5 quad_perm:[1,1,3,3] row_mask:0xf bank_mask:0xf bound_ctrl:1
	v_mul_f32_dpp v9, v65, v120 quad_perm:[1,1,3,3] row_mask:0xf bank_mask:0xf bound_ctrl:1
	v_fmac_f32_dpp v6, v48, v2 quad_perm:[0,0,2,2] row_mask:0xf bank_mask:0xf bound_ctrl:1
	v_add_f32_dpp v10, v10, v10 quad_perm:[2,3,0,1] row_mask:0xf bank_mask:0xf bound_ctrl:1
	v_fmac_f32_dpp v7, v49, v3 quad_perm:[0,0,2,2] row_mask:0xf bank_mask:0xf bound_ctrl:1
	v_fmac_f32_dpp v8, v48, v4 quad_perm:[1,1,3,3] row_mask:0xf bank_mask:0xf bound_ctrl:1
	v_add_f32_dpp v10, v10, v10 row_ror:4 row_mask:0xf bank_mask:0xf bound_ctrl:1
	v_fmac_f32_dpp v9, v49, v5 quad_perm:[1,1,3,3] row_mask:0xf bank_mask:0xf bound_ctrl:1
	v_mul_f32_dpp v13, v78, v2 quad_perm:[0,0,2,2] row_mask:0xf bank_mask:0xf bound_ctrl:1
	v_add_f32_dpp v10, v10, v10 row_ror:8 row_mask:0xf bank_mask:0xf bound_ctrl:1
	v_mov_b32_e32 v14, v10
	v_fmac_f32_dpp v13, v79, v3 quad_perm:[0,0,2,2] row_mask:0xf bank_mask:0xf bound_ctrl:1
	v_fmac_f32_dpp v13, v78, v4 quad_perm:[1,1,3,3] row_mask:0xf bank_mask:0xf bound_ctrl:1
	v_permlane16_swap_b32 v10, v14
	v_add_f32_e32 v10, v10, v14
	v_fmac_f32_dpp v6, v56, v10 quad_perm:[0,0,2,2] row_mask:0xf bank_mask:0xf bound_ctrl:1
	v_fmac_f32_dpp v7, v57, v10 quad_perm:[0,0,2,2] row_mask:0xf bank_mask:0xf bound_ctrl:1
	v_fmac_f32_dpp v8, v56, v10 quad_perm:[1,1,3,3] row_mask:0xf bank_mask:0xf bound_ctrl:1
	v_fmac_f32_dpp v9, v57, v10 quad_perm:[1,1,3,3] row_mask:0xf bank_mask:0xf bound_ctrl:1
	v_fmac_f32_dpp v13, v79, v5 quad_perm:[1,1,3,3] row_mask:0xf bank_mask:0xf bound_ctrl:1
	ds_write2st64_b32 v30, v12, v13 offset0:6 offset1:7
	ds_read_b64 v[44:45], v35 offset:31232
	ds_read_b64 v[52:53], v35 offset:14848
	ds_read_b64 v[60:61], v35 offset:39424
	ds_read_b64 v[68:69], v35 offset:23040
	ds_read_b64 v[76:77], v35 offset:6656
	ds_read2_b32 v[122:123], v38 offset0:160 offset1:176
	s_waitcnt lgkmcnt(7)
; __device__ __forceinline__ float allreduce16(float x) { x += dppf(x, 0); x += dppf(x, 1); x += dppf(x, 2); x += dppf(x, 3); return x; }
; __device__ void rw_scan(const Params& p, int l, unsigned char* shm, int item) {
;     ...
;                 for (int s2 = 0; s2 < 16; ++s2) {
;                     const int s = hs * 16 + s2, sn = (s + 1) & (TC - 1);
;                     const f32x4 na4 = *(const f32x4*)(sr + 3 * 2048 + sn * 64), nw4 = *(const f32x4*)(sr + 2048 + sn * 64), nb4 = *(const f32x4*)(sr + 4 * 2048 + sn * 64), nk4 = *(const f32x4*)(sr + 2 * 2048 + sn * 64), nr4 = *(const f32x4*)(sr + sn * 64);
;                     const float nvv = sv[sn * 16];
;                     f32x2 tq = S01 * (f32x2){a4[0], a4[1]}; tq = S23 * (f32x2){a4[2], a4[3]} + tq;
;                     const float sav = allreduce16(tq[0] + tq[1]);
;                     f32x2 u0 = (f32x2){b4[0], b4[1]} * sav, u1 = (f32x2){b4[2], b4[3]} * sav;
;                     u0 = (f32x2){k4[0], k4[1]} * vv + u0; u1 = (f32x2){k4[2], k4[3]} * vv + u1;
;                     S01 = S01 * (f32x2){w4[0], w4[1]} + u0; S23 = S23 * (f32x2){w4[2], w4[3]} + u1;
;                     f32x2 oq = S01 * (f32x2){r4[0], r4[1]}; oq = S23 * (f32x2){r4[2], r4[3]} + oq;
;                     pp[s2 * 64] = oq[0] + oq[1];
;                     a4 = na4; w4 = nw4; b4 = nb4; k4 = nk4; r4 = nr4; vv = nvv;
	v_mul_f32_dpp v11, v42, v6 quad_perm:[0,0,2,2] row_mask:0xf bank_mask:0xf bound_ctrl:1
	v_mul_f32_dpp v2, v66, v121 quad_perm:[0,0,2,2] row_mask:0xf bank_mask:0xf bound_ctrl:1
	v_fmac_f32_dpp v11, v43, v7 quad_perm:[0,0,2,2] row_mask:0xf bank_mask:0xf bound_ctrl:1
	v_mul_f32_dpp v3, v67, v121 quad_perm:[0,0,2,2] row_mask:0xf bank_mask:0xf bound_ctrl:1
	v_fmac_f32_dpp v11, v42, v8 quad_perm:[1,1,3,3] row_mask:0xf bank_mask:0xf bound_ctrl:1
	v_mul_f32_dpp v4, v66, v121 quad_perm:[1,1,3,3] row_mask:0xf bank_mask:0xf bound_ctrl:1
	v_fmac_f32_dpp v11, v43, v9 quad_perm:[1,1,3,3] row_mask:0xf bank_mask:0xf bound_ctrl:1
	v_mul_f32_dpp v5, v67, v121 quad_perm:[1,1,3,3] row_mask:0xf bank_mask:0xf bound_ctrl:1
	v_fmac_f32_dpp v2, v50, v6 quad_perm:[0,0,2,2] row_mask:0xf bank_mask:0xf bound_ctrl:1
	v_add_f32_dpp v11, v11, v11 quad_perm:[2,3,0,1] row_mask:0xf bank_mask:0xf bound_ctrl:1
	v_fmac_f32_dpp v3, v51, v7 quad_perm:[0,0,2,2] row_mask:0xf bank_mask:0xf bound_ctrl:1
	v_fmac_f32_dpp v4, v50, v8 quad_perm:[1,1,3,3] row_mask:0xf bank_mask:0xf bound_ctrl:1
	v_add_f32_dpp v11, v11, v11 row_ror:4 row_mask:0xf bank_mask:0xf bound_ctrl:1
	v_fmac_f32_dpp v5, v51, v9 quad_perm:[1,1,3,3] row_mask:0xf bank_mask:0xf bound_ctrl:1
	v_mul_f32_dpp v12, v72, v6 quad_perm:[0,0,2,2] row_mask:0xf bank_mask:0xf bound_ctrl:1
	v_add_f32_dpp v11, v11, v11 row_ror:8 row_mask:0xf bank_mask:0xf bound_ctrl:1
	v_mov_b32_e32 v15, v11
	v_fmac_f32_dpp v12, v73, v7 quad_perm:[0,0,2,2] row_mask:0xf bank_mask:0xf bound_ctrl:1
	v_fmac_f32_dpp v12, v72, v8 quad_perm:[1,1,3,3] row_mask:0xf bank_mask:0xf bound_ctrl:1
	v_permlane16_swap_b32 v11, v15
	v_add_f32_e32 v11, v11, v15
	v_fmac_f32_dpp v2, v58, v11 quad_perm:[0,0,2,2] row_mask:0xf bank_mask:0xf bound_ctrl:1
	v_fmac_f32_dpp v3, v59, v11 quad_perm:[0,0,2,2] row_mask:0xf bank_mask:0xf bound_ctrl:1
	v_fmac_f32_dpp v4, v58, v11 quad_perm:[1,1,3,3] row_mask:0xf bank_mask:0xf bound_ctrl:1
	v_fmac_f32_dpp v5, v59, v11 quad_perm:[1,1,3,3] row_mask:0xf bank_mask:0xf bound_ctrl:1
	v_fmac_f32_dpp v12, v73, v9 quad_perm:[1,1,3,3] row_mask:0xf bank_mask:0xf bound_ctrl:1
	ds_read_b64 v[46:47], v35 offset:31488
	ds_read_b64 v[54:55], v35 offset:15104
	ds_read_b64 v[62:63], v35 offset:39680
	ds_read_b64 v[70:71], v35 offset:23296
	ds_read_b64 v[78:79], v35 offset:6912
	s_waitcnt lgkmcnt(5)
	v_mul_f32_dpp v10, v44, v2 quad_perm:[0,0,2,2] row_mask:0xf bank_mask:0xf bound_ctrl:1
	v_mul_f32_dpp v6, v68, v122 quad_perm:[0,0,2,2] row_mask:0xf bank_mask:0xf bound_ctrl:1
	v_fmac_f32_dpp v10, v45, v3 quad_perm:[0,0,2,2] row_mask:0xf bank_mask:0xf bound_ctrl:1
	v_mul_f32_dpp v7, v69, v122 quad_perm:[0,0,2,2] row_mask:0xf bank_mask:0xf bound_ctrl:1
	v_fmac_f32_dpp v10, v44, v4 quad_perm:[1,1,3,3] row_mask:0xf bank_mask:0xf bound_ctrl:1
	v_mul_f32_dpp v8, v68, v122 quad_perm:[1,1,3,3] row_mask:0xf bank_mask:0xf bound_ctrl:1
	v_fmac_f32_dpp v10, v45, v5 quad_perm:[1,1,3,3] row_mask:0xf bank_mask:0xf bound_ctrl:1
	v_mul_f32_dpp v9, v69, v122 quad_perm:[1,1,3,3] row_mask:0xf bank_mask:0xf bound_ctrl:1
	v_fmac_f32_dpp v6, v52, v2 quad_perm:[0,0,2,2] row_mask:0xf bank_mask:0xf bound_ctrl:1
	v_add_f32_dpp v10, v10, v10 quad_perm:[2,3,0,1] row_mask:0xf bank_mask:0xf bound_ctrl:1
	v_fmac_f32_dpp v7, v53, v3 quad_perm:[0,0,2,2] row_mask:0xf bank_mask:0xf bound_ctrl:1
	v_fmac_f32_dpp v8, v52, v4 quad_perm:[1,1,3,3] row_mask:0xf bank_mask:0xf bound_ctrl:1
	v_add_f32_dpp v10, v10, v10 row_ror:4 row_mask:0xf bank_mask:0xf bound_ctrl:1
	v_fmac_f32_dpp v9, v53, v5 quad_perm:[1,1,3,3] row_mask:0xf bank_mask:0xf bound_ctrl:1
	v_mul_f32_dpp v13, v74, v2 quad_perm:[0,0,2,2] row_mask:0xf bank_mask:0xf bound_ctrl:1
	v_add_f32_dpp v10, v10, v10 row_ror:8 row_mask:0xf bank_mask:0xf bound_ctrl:1
	v_mov_b32_e32 v14, v10
	v_fmac_f32_dpp v13, v75, v3 quad_perm:[0,0,2,2] row_mask:0xf bank_mask:0xf bound_ctrl:1
	v_fmac_f32_dpp v13, v74, v4 quad_perm:[1,1,3,3] row_mask:0xf bank_mask:0xf bound_ctrl:1
	v_permlane16_swap_b32 v10, v14
	v_add_f32_e32 v10, v10, v14
	v_fmac_f32_dpp v6, v60, v10 quad_perm:[0,0,2,2] row_mask:0xf bank_mask:0xf bound_ctrl:1
	v_fmac_f32_dpp v7, v61, v10 quad_perm:[0,0,2,2] row_mask:0xf bank_mask:0xf bound_ctrl:1
	v_fmac_f32_dpp v8, v60, v10 quad_perm:[1,1,3,3] row_mask:0xf bank_mask:0xf bound_ctrl:1
	v_fmac_f32_dpp v9, v61, v10 quad_perm:[1,1,3,3] row_mask:0xf bank_mask:0xf bound_ctrl:1
	v_fmac_f32_dpp v13, v75, v5 quad_perm:[1,1,3,3] row_mask:0xf bank_mask:0xf bound_ctrl:1
	ds_write2st64_b32 v30, v12, v13 offset0:8 offset1:9
	ds_read_b64 v[40:41], v35 offset:31744
	ds_read_b64 v[48:49], v35 offset:15360
	ds_read_b64 v[56:57], v35 offset:39936
	ds_read_b64 v[64:65], v35 offset:23552
	ds_read_b64 v[72:73], v35 offset:7168
	ds_read2_b32 v[124:125], v38 offset0:192 offset1:208
	s_waitcnt lgkmcnt(7)
; __device__ __forceinline__ float allreduce16(float x) { x += dppf(x, 0); x += dppf(x, 1); x += dppf(x, 2); x += dppf(x, 3); return x; }
; __device__ void rw_scan(const Params& p, int l, unsigned char* shm, int item) {
;     ...
;                 for (int s2 = 0; s2 < 16; ++s2) {
;                     const int s = hs * 16 + s2, sn = (s + 1) & (TC - 1);
;                     const f32x4 na4 = *(const f32x4*)(sr + 3 * 2048 + sn * 64), nw4 = *(const f32x4*)(sr + 2048 + sn * 64), nb4 = *(const f32x4*)(sr + 4 * 2048 + sn * 64), nk4 = *(const f32x4*)(sr + 2 * 2048 + sn * 64), nr4 = *(const f32x4*)(sr + sn * 64);
;                     const float nvv = sv[sn * 16];
;                     f32x2 tq = S01 * (f32x2){a4[0], a4[1]}; tq = S23 * (f32x2){a4[2], a4[3]} + tq;
;                     const float sav = allreduce16(tq[0] + tq[1]);
;                     f32x2 u0 = (f32x2){b4[0], b4[1]} * sav, u1 = (f32x2){b4[2], b4[3]} * sav;
;                     u0 = (f32x2){k4[0], k4[1]} * vv + u0; u1 = (f32x2){k4[2], k4[3]} * vv + u1;
;                     S01 = S01 * (f32x2){w4[0], w4[1]} + u0; S23 = S23 * (f32x2){w4[2], w4[3]} + u1;
;                     f32x2 oq = S01 * (f32x2){r4[0], r4[1]}; oq = S23 * (f32x2){r4[2], r4[3]} + oq;
;                     pp[s2 * 64] = oq[0] + oq[1];
;                     a4 = na4; w4 = nw4; b4 = nb4; k4 = nk4; r4 = nr4; vv = nvv;
	v_mul_f32_dpp v11, v46, v6 quad_perm:[0,0,2,2] row_mask:0xf bank_mask:0xf bound_ctrl:1
	v_mul_f32_dpp v2, v70, v123 quad_perm:[0,0,2,2] row_mask:0xf bank_mask:0xf bound_ctrl:1
	v_fmac_f32_dpp v11, v47, v7 quad_perm:[0,0,2,2] row_mask:0xf bank_mask:0xf bound_ctrl:1
	v_mul_f32_dpp v3, v71, v123 quad_perm:[0,0,2,2] row_mask:0xf bank_mask:0xf bound_ctrl:1
	v_fmac_f32_dpp v11, v46, v8 quad_perm:[1,1,3,3] row_mask:0xf bank_mask:0xf bound_ctrl:1
	v_mul_f32_dpp v4, v70, v123 quad_perm:[1,1,3,3] row_mask:0xf bank_mask:0xf bound_ctrl:1
	v_fmac_f32_dpp v11, v47, v9 quad_perm:[1,1,3,3] row_mask:0xf bank_mask:0xf bound_ctrl:1
	v_mul_f32_dpp v5, v71, v123 quad_perm:[1,1,3,3] row_mask:0xf bank_mask:0xf bound_ctrl:1
	v_fmac_f32_dpp v2, v54, v6 quad_perm:[0,0,2,2] row_mask:0xf bank_mask:0xf bound_ctrl:1
	v_add_f32_dpp v11, v11, v11 quad_perm:[2,3,0,1] row_mask:0xf bank_mask:0xf bound_ctrl:1
	v_fmac_f32_dpp v3, v55, v7 quad_perm:[0,0,2,2] row_mask:0xf bank_mask:0xf bound_ctrl:1
	v_fmac_f32_dpp v4, v54, v8 quad_perm:[1,1,3,3] row_mask:0xf bank_mask:0xf bound_ctrl:1
	v_add_f32_dpp v11, v11, v11 row_ror:4 row_mask:0xf bank_mask:0xf bound_ctrl:1
	v_fmac_f32_dpp v5, v55, v9 quad_perm:[1,1,3,3] row_mask:0xf bank_mask:0xf bound_ctrl:1
	v_mul_f32_dpp v12, v76, v6 quad_perm:[0,0,2,2] row_mask:0xf bank_mask:0xf bound_ctrl:1
	v_add_f32_dpp v11, v11, v11 row_ror:8 row_mask:0xf bank_mask:0xf bound_ctrl:1
	v_mov_b32_e32 v15, v11
	v_fmac_f32_dpp v12, v77, v7 quad_perm:[0,0,2,2] row_mask:0xf bank_mask:0xf bound_ctrl:1
	v_fmac_f32_dpp v12, v76, v8 quad_perm:[1,1,3,3] row_mask:0xf bank_mask:0xf bound_ctrl:1
	v_permlane16_swap_b32 v11, v15
	v_add_f32_e32 v11, v11, v15
	v_fmac_f32_dpp v2, v62, v11 quad_perm:[0,0,2,2] row_mask:0xf bank_mask:0xf bound_ctrl:1
	v_fmac_f32_dpp v3, v63, v11 quad_perm:[0,0,2,2] row_mask:0xf bank_mask:0xf bound_ctrl:1
	v_fmac_f32_dpp v4, v62, v11 quad_perm:[1,1,3,3] row_mask:0xf bank_mask:0xf bound_ctrl:1
	v_fmac_f32_dpp v5, v63, v11 quad_perm:[1,1,3,3] row_mask:0xf bank_mask:0xf bound_ctrl:1
	v_fmac_f32_dpp v12, v77, v9 quad_perm:[1,1,3,3] row_mask:0xf bank_mask:0xf bound_ctrl:1
	ds_read_b64 v[42:43], v35 offset:32000
	ds_read_b64 v[50:51], v35 offset:15616
	ds_read_b64 v[58:59], v35 offset:40192
	ds_read_b64 v[66:67], v35 offset:23808
	ds_read_b64 v[74:75], v35 offset:7424
	s_waitcnt lgkmcnt(5)
	v_mul_f32_dpp v10, v40, v2 quad_perm:[0,0,2,2] row_mask:0xf bank_mask:0xf bound_ctrl:1
	v_mul_f32_dpp v6, v64, v124 quad_perm:[0,0,2,2] row_mask:0xf bank_mask:0xf bound_ctrl:1
	v_fmac_f32_dpp v10, v41, v3 quad_perm:[0,0,2,2] row_mask:0xf bank_mask:0xf bound_ctrl:1
	v_mul_f32_dpp v7, v65, v124 quad_perm:[0,0,2,2] row_mask:0xf bank_mask:0xf bound_ctrl:1
	v_fmac_f32_dpp v10, v40, v4 quad_perm:[1,1,3,3] row_mask:0xf bank_mask:0xf bound_ctrl:1
	v_mul_f32_dpp v8, v64, v124 quad_perm:[1,1,3,3] row_mask:0xf bank_mask:0xf bound_ctrl:1
	v_fmac_f32_dpp v10, v41, v5 quad_perm:[1,1,3,3] row_mask:0xf bank_mask:0xf bound_ctrl:1
	v_mul_f32_dpp v9, v65, v124 quad_perm:[1,1,3,3] row_mask:0xf bank_mask:0xf bound_ctrl:1
	v_fmac_f32_dpp v6, v48, v2 quad_perm:[0,0,2,2] row_mask:0xf bank_mask:0xf bound_ctrl:1
	v_add_f32_dpp v10, v10, v10 quad_perm:[2,3,0,1] row_mask:0xf bank_mask:0xf bound_ctrl:1
	v_fmac_f32_dpp v7, v49, v3 quad_perm:[0,0,2,2] row_mask:0xf bank_mask:0xf bound_ctrl:1
	v_fmac_f32_dpp v8, v48, v4 quad_perm:[1,1,3,3] row_mask:0xf bank_mask:0xf bound_ctrl:1
	v_add_f32_dpp v10, v10, v10 row_ror:4 row_mask:0xf bank_mask:0xf bound_ctrl:1
	v_fmac_f32_dpp v9, v49, v5 quad_perm:[1,1,3,3] row_mask:0xf bank_mask:0xf bound_ctrl:1
	v_mul_f32_dpp v13, v78, v2 quad_perm:[0,0,2,2] row_mask:0xf bank_mask:0xf bound_ctrl:1
	v_add_f32_dpp v10, v10, v10 row_ror:8 row_mask:0xf bank_mask:0xf bound_ctrl:1
	v_mov_b32_e32 v14, v10
	v_fmac_f32_dpp v13, v79, v3 quad_perm:[0,0,2,2] row_mask:0xf bank_mask:0xf bound_ctrl:1
	v_fmac_f32_dpp v13, v78, v4 quad_perm:[1,1,3,3] row_mask:0xf bank_mask:0xf bound_ctrl:1
	v_permlane16_swap_b32 v10, v14
	v_add_f32_e32 v10, v10, v14
	v_fmac_f32_dpp v6, v56, v10 quad_perm:[0,0,2,2] row_mask:0xf bank_mask:0xf bound_ctrl:1
	v_fmac_f32_dpp v7, v57, v10 quad_perm:[0,0,2,2] row_mask:0xf bank_mask:0xf bound_ctrl:1
	v_fmac_f32_dpp v8, v56, v10 quad_perm:[1,1,3,3] row_mask:0xf bank_mask:0xf bound_ctrl:1
	v_fmac_f32_dpp v9, v57, v10 quad_perm:[1,1,3,3] row_mask:0xf bank_mask:0xf bound_ctrl:1
	v_fmac_f32_dpp v13, v79, v5 quad_perm:[1,1,3,3] row_mask:0xf bank_mask:0xf bound_ctrl:1
	ds_write2st64_b32 v30, v12, v13 offset0:10 offset1:11
	ds_read_b64 v[44:45], v35 offset:32256
	ds_read_b64 v[52:53], v35 offset:15872
	ds_read_b64 v[60:61], v35 offset:40448
	ds_read_b64 v[68:69], v35 offset:24064
	ds_read_b64 v[76:77], v35 offset:7680
	ds_read2_b32 v[120:121], v38 offset0:224 offset1:240
	s_waitcnt lgkmcnt(7)
; __device__ __forceinline__ float allreduce16(float x) { x += dppf(x, 0); x += dppf(x, 1); x += dppf(x, 2); x += dppf(x, 3); return x; }
; __device__ void rw_scan(const Params& p, int l, unsigned char* shm, int item) {
;     ...
;                 for (int s2 = 0; s2 < 16; ++s2) {
;                     const int s = hs * 16 + s2, sn = (s + 1) & (TC - 1);
;                     const f32x4 na4 = *(const f32x4*)(sr + 3 * 2048 + sn * 64), nw4 = *(const f32x4*)(sr + 2048 + sn * 64), nb4 = *(const f32x4*)(sr + 4 * 2048 + sn * 64), nk4 = *(const f32x4*)(sr + 2 * 2048 + sn * 64), nr4 = *(const f32x4*)(sr + sn * 64);
;                     const float nvv = sv[sn * 16];
;                     f32x2 tq = S01 * (f32x2){a4[0], a4[1]}; tq = S23 * (f32x2){a4[2], a4[3]} + tq;
;                     const float sav = allreduce16(tq[0] + tq[1]);
;                     f32x2 u0 = (f32x2){b4[0], b4[1]} * sav, u1 = (f32x2){b4[2], b4[3]} * sav;
;                     u0 = (f32x2){k4[0], k4[1]} * vv + u0; u1 = (f32x2){k4[2], k4[3]} * vv + u1;
;                     S01 = S01 * (f32x2){w4[0], w4[1]} + u0; S23 = S23 * (f32x2){w4[2], w4[3]} + u1;
;                     f32x2 oq = S01 * (f32x2){r4[0], r4[1]}; oq = S23 * (f32x2){r4[2], r4[3]} + oq;
;                     pp[s2 * 64] = oq[0] + oq[1];
;                     a4 = na4; w4 = nw4; b4 = nb4; k4 = nk4; r4 = nr4; vv = nvv;
	v_mul_f32_dpp v11, v42, v6 quad_perm:[0,0,2,2] row_mask:0xf bank_mask:0xf bound_ctrl:1
	v_mul_f32_dpp v2, v66, v125 quad_perm:[0,0,2,2] row_mask:0xf bank_mask:0xf bound_ctrl:1
	v_fmac_f32_dpp v11, v43, v7 quad_perm:[0,0,2,2] row_mask:0xf bank_mask:0xf bound_ctrl:1
	v_mul_f32_dpp v3, v67, v125 quad_perm:[0,0,2,2] row_mask:0xf bank_mask:0xf bound_ctrl:1
	v_fmac_f32_dpp v11, v42, v8 quad_perm:[1,1,3,3] row_mask:0xf bank_mask:0xf bound_ctrl:1
	v_mul_f32_dpp v4, v66, v125 quad_perm:[1,1,3,3] row_mask:0xf bank_mask:0xf bound_ctrl:1
	v_fmac_f32_dpp v11, v43, v9 quad_perm:[1,1,3,3] row_mask:0xf bank_mask:0xf bound_ctrl:1
	v_mul_f32_dpp v5, v67, v125 quad_perm:[1,1,3,3] row_mask:0xf bank_mask:0xf bound_ctrl:1
	v_fmac_f32_dpp v2, v50, v6 quad_perm:[0,0,2,2] row_mask:0xf bank_mask:0xf bound_ctrl:1
	v_add_f32_dpp v11, v11, v11 quad_perm:[2,3,0,1] row_mask:0xf bank_mask:0xf bound_ctrl:1
	v_fmac_f32_dpp v3, v51, v7 quad_perm:[0,0,2,2] row_mask:0xf bank_mask:0xf bound_ctrl:1
	v_fmac_f32_dpp v4, v50, v8 quad_perm:[1,1,3,3] row_mask:0xf bank_mask:0xf bound_ctrl:1
	v_add_f32_dpp v11, v11, v11 row_ror:4 row_mask:0xf bank_mask:0xf bound_ctrl:1
	v_fmac_f32_dpp v5, v51, v9 quad_perm:[1,1,3,3] row_mask:0xf bank_mask:0xf bound_ctrl:1
	v_mul_f32_dpp v12, v72, v6 quad_perm:[0,0,2,2] row_mask:0xf bank_mask:0xf bound_ctrl:1
	v_add_f32_dpp v11, v11, v11 row_ror:8 row_mask:0xf bank_mask:0xf bound_ctrl:1
	v_mov_b32_e32 v15, v11
	v_fmac_f32_dpp v12, v73, v7 quad_perm:[0,0,2,2] row_mask:0xf bank_mask:0xf bound_ctrl:1
	v_fmac_f32_dpp v12, v72, v8 quad_perm:[1,1,3,3] row_mask:0xf bank_mask:0xf bound_ctrl:1
	v_permlane16_swap_b32 v11, v15
	v_add_f32_e32 v11, v11, v15
	v_fmac_f32_dpp v2, v58, v11 quad_perm:[0,0,2,2] row_mask:0xf bank_mask:0xf bound_ctrl:1
	v_fmac_f32_dpp v3, v59, v11 quad_perm:[0,0,2,2] row_mask:0xf bank_mask:0xf bound_ctrl:1
	v_fmac_f32_dpp v4, v58, v11 quad_perm:[1,1,3,3] row_mask:0xf bank_mask:0xf bound_ctrl:1
	v_fmac_f32_dpp v5, v59, v11 quad_perm:[1,1,3,3] row_mask:0xf bank_mask:0xf bound_ctrl:1
	v_fmac_f32_dpp v12, v73, v9 quad_perm:[1,1,3,3] row_mask:0xf bank_mask:0xf bound_ctrl:1
	ds_read_b64 v[46:47], v35 offset:32512
	ds_read_b64 v[54:55], v35 offset:16128
	ds_read_b64 v[62:63], v35 offset:40704
	ds_read_b64 v[70:71], v35 offset:24320
	ds_read_b64 v[78:79], v35 offset:7936
	s_waitcnt lgkmcnt(5)
	v_mul_f32_dpp v10, v44, v2 quad_perm:[0,0,2,2] row_mask:0xf bank_mask:0xf bound_ctrl:1
	v_mul_f32_dpp v6, v68, v120 quad_perm:[0,0,2,2] row_mask:0xf bank_mask:0xf bound_ctrl:1
	v_fmac_f32_dpp v10, v45, v3 quad_perm:[0,0,2,2] row_mask:0xf bank_mask:0xf bound_ctrl:1
	v_mul_f32_dpp v7, v69, v120 quad_perm:[0,0,2,2] row_mask:0xf bank_mask:0xf bound_ctrl:1
	v_fmac_f32_dpp v10, v44, v4 quad_perm:[1,1,3,3] row_mask:0xf bank_mask:0xf bound_ctrl:1
	v_mul_f32_dpp v8, v68, v120 quad_perm:[1,1,3,3] row_mask:0xf bank_mask:0xf bound_ctrl:1
	v_fmac_f32_dpp v10, v45, v5 quad_perm:[1,1,3,3] row_mask:0xf bank_mask:0xf bound_ctrl:1
	v_mul_f32_dpp v9, v69, v120 quad_perm:[1,1,3,3] row_mask:0xf bank_mask:0xf bound_ctrl:1
	v_fmac_f32_dpp v6, v52, v2 quad_perm:[0,0,2,2] row_mask:0xf bank_mask:0xf bound_ctrl:1
	v_add_f32_dpp v10, v10, v10 quad_perm:[2,3,0,1] row_mask:0xf bank_mask:0xf bound_ctrl:1
	v_fmac_f32_dpp v7, v53, v3 quad_perm:[0,0,2,2] row_mask:0xf bank_mask:0xf bound_ctrl:1
	v_fmac_f32_dpp v8, v52, v4 quad_perm:[1,1,3,3] row_mask:0xf bank_mask:0xf bound_ctrl:1
	v_add_f32_dpp v10, v10, v10 row_ror:4 row_mask:0xf bank_mask:0xf bound_ctrl:1
	v_fmac_f32_dpp v9, v53, v5 quad_perm:[1,1,3,3] row_mask:0xf bank_mask:0xf bound_ctrl:1
	v_mul_f32_dpp v13, v74, v2 quad_perm:[0,0,2,2] row_mask:0xf bank_mask:0xf bound_ctrl:1
	v_add_f32_dpp v10, v10, v10 row_ror:8 row_mask:0xf bank_mask:0xf bound_ctrl:1
	v_mov_b32_e32 v14, v10
	v_fmac_f32_dpp v13, v75, v3 quad_perm:[0,0,2,2] row_mask:0xf bank_mask:0xf bound_ctrl:1
	v_fmac_f32_dpp v13, v74, v4 quad_perm:[1,1,3,3] row_mask:0xf bank_mask:0xf bound_ctrl:1
	v_permlane16_swap_b32 v10, v14
	v_add_f32_e32 v10, v10, v14
	v_fmac_f32_dpp v6, v60, v10 quad_perm:[0,0,2,2] row_mask:0xf bank_mask:0xf bound_ctrl:1
	v_fmac_f32_dpp v7, v61, v10 quad_perm:[0,0,2,2] row_mask:0xf bank_mask:0xf bound_ctrl:1
	v_fmac_f32_dpp v8, v60, v10 quad_perm:[1,1,3,3] row_mask:0xf bank_mask:0xf bound_ctrl:1
	v_fmac_f32_dpp v9, v61, v10 quad_perm:[1,1,3,3] row_mask:0xf bank_mask:0xf bound_ctrl:1
	v_fmac_f32_dpp v13, v75, v5 quad_perm:[1,1,3,3] row_mask:0xf bank_mask:0xf bound_ctrl:1
	ds_write2st64_b32 v30, v12, v13 offset0:12 offset1:13
	s_waitcnt lgkmcnt(1)
; __device__ __forceinline__ float allreduce16(float x) { x += dppf(x, 0); x += dppf(x, 1); x += dppf(x, 2); x += dppf(x, 3); return x; }
; __device__ void rw_scan(const Params& p, int l, unsigned char* shm, int item) {
;     ...
;                 for (int s2 = 0; s2 < 16; ++s2) {
;                     const int s = hs * 16 + s2, sn = (s + 1) & (TC - 1);
;                     const f32x4 na4 = *(const f32x4*)(sr + 3 * 2048 + sn * 64), nw4 = *(const f32x4*)(sr + 2048 + sn * 64), nb4 = *(const f32x4*)(sr + 4 * 2048 + sn * 64), nk4 = *(const f32x4*)(sr + 2 * 2048 + sn * 64), nr4 = *(const f32x4*)(sr + sn * 64);
;                     const float nvv = sv[sn * 16];
;                     f32x2 tq = S01 * (f32x2){a4[0], a4[1]}; tq = S23 * (f32x2){a4[2], a4[3]} + tq;
;                     const float sav = allreduce16(tq[0] + tq[1]);
;                     f32x2 u0 = (f32x2){b4[0], b4[1]} * sav, u1 = (f32x2){b4[2], b4[3]} * sav;
;                     u0 = (f32x2){k4[0], k4[1]} * vv + u0; u1 = (f32x2){k4[2], k4[3]} * vv + u1;
;                     S01 = S01 * (f32x2){w4[0], w4[1]} + u0; S23 = S23 * (f32x2){w4[2], w4[3]} + u1;
;                     f32x2 oq = S01 * (f32x2){r4[0], r4[1]}; oq = S23 * (f32x2){r4[2], r4[3]} + oq;
;                     pp[s2 * 64] = oq[0] + oq[1];
;                     a4 = na4; w4 = nw4; b4 = nb4; k4 = nk4; r4 = nr4; vv = nvv;
;                 }
;                 { const int s2 = lane >> 2, rr = lane & 3; const float* q_ = part + w * 1024 + s2 * 64 + rr * 16;
;                   const f32x4 x0 = *(const f32x4*)q_, x1 = *(const f32x4*)(q_ + 4), x2 = *(const f32x4*)(q_ + 8), x3 = *(const f32x4*)(q_ + 12);
;                   const float ov = ((x0[0] + x0[1]) + (x0[2] + x0[3])) + ((x1[0] + x1[1]) + (x1[2] + x1[3])) + ((x2[0] + x2[1]) + (x2[2] + x2[3])) + ((x3[0] + x3[1]) + (x3[2] + x3[3]));
;                   const int st2 = ck * TC + hs * 16 + s2; const int t2 = d ? (T - 1 - st2) : st2;
;                   yout[(size_t)(b * T + t2) * 768 + h * 64 + quarter * 16 + w * 4 + rr] = ov; }
;             }
;             __syncthreads();
;         }
;         __builtin_amdgcn_s_setprio(0);
	v_mul_f32_dpp v11, v46, v6 quad_perm:[0,0,2,2] row_mask:0xf bank_mask:0xf bound_ctrl:1
	v_mul_f32_dpp v2, v70, v121 quad_perm:[0,0,2,2] row_mask:0xf bank_mask:0xf bound_ctrl:1
	v_fmac_f32_dpp v11, v47, v7 quad_perm:[0,0,2,2] row_mask:0xf bank_mask:0xf bound_ctrl:1
	v_mul_f32_dpp v3, v71, v121 quad_perm:[0,0,2,2] row_mask:0xf bank_mask:0xf bound_ctrl:1
	v_fmac_f32_dpp v11, v46, v8 quad_perm:[1,1,3,3] row_mask:0xf bank_mask:0xf bound_ctrl:1
	v_mul_f32_dpp v4, v70, v121 quad_perm:[1,1,3,3] row_mask:0xf bank_mask:0xf bound_ctrl:1
	v_fmac_f32_dpp v11, v47, v9 quad_perm:[1,1,3,3] row_mask:0xf bank_mask:0xf bound_ctrl:1
	v_mul_f32_dpp v5, v71, v121 quad_perm:[1,1,3,3] row_mask:0xf bank_mask:0xf bound_ctrl:1
	v_fmac_f32_dpp v2, v54, v6 quad_perm:[0,0,2,2] row_mask:0xf bank_mask:0xf bound_ctrl:1
	v_add_f32_dpp v11, v11, v11 quad_perm:[2,3,0,1] row_mask:0xf bank_mask:0xf bound_ctrl:1
	v_fmac_f32_dpp v3, v55, v7 quad_perm:[0,0,2,2] row_mask:0xf bank_mask:0xf bound_ctrl:1
	v_fmac_f32_dpp v4, v54, v8 quad_perm:[1,1,3,3] row_mask:0xf bank_mask:0xf bound_ctrl:1
	v_add_f32_dpp v11, v11, v11 row_ror:4 row_mask:0xf bank_mask:0xf bound_ctrl:1
	v_fmac_f32_dpp v5, v55, v9 quad_perm:[1,1,3,3] row_mask:0xf bank_mask:0xf bound_ctrl:1
	v_mul_f32_dpp v12, v76, v6 quad_perm:[0,0,2,2] row_mask:0xf bank_mask:0xf bound_ctrl:1
	v_add_f32_dpp v11, v11, v11 row_ror:8 row_mask:0xf bank_mask:0xf bound_ctrl:1
	v_mov_b32_e32 v15, v11
	v_fmac_f32_dpp v12, v77, v7 quad_perm:[0,0,2,2] row_mask:0xf bank_mask:0xf bound_ctrl:1
	v_fmac_f32_dpp v12, v76, v8 quad_perm:[1,1,3,3] row_mask:0xf bank_mask:0xf bound_ctrl:1
	v_permlane16_swap_b32 v11, v15
	v_add_f32_e32 v11, v11, v15
	v_fmac_f32_dpp v2, v62, v11 quad_perm:[0,0,2,2] row_mask:0xf bank_mask:0xf bound_ctrl:1
	v_fmac_f32_dpp v3, v63, v11 quad_perm:[0,0,2,2] row_mask:0xf bank_mask:0xf bound_ctrl:1
	v_fmac_f32_dpp v4, v62, v11 quad_perm:[1,1,3,3] row_mask:0xf bank_mask:0xf bound_ctrl:1
	v_fmac_f32_dpp v5, v63, v11 quad_perm:[1,1,3,3] row_mask:0xf bank_mask:0xf bound_ctrl:1
	v_fmac_f32_dpp v12, v77, v9 quad_perm:[1,1,3,3] row_mask:0xf bank_mask:0xf bound_ctrl:1
	v_mul_f32_dpp v13, v78, v2 quad_perm:[0,0,2,2] row_mask:0xf bank_mask:0xf bound_ctrl:1
	s_add_i32 s3, s3, 1
	v_fmac_f32_dpp v13, v79, v3 quad_perm:[0,0,2,2] row_mask:0xf bank_mask:0xf bound_ctrl:1
	s_cmpk_eq_i32 s3, 0x200
	v_fmac_f32_dpp v13, v78, v4 quad_perm:[1,1,3,3] row_mask:0xf bank_mask:0xf bound_ctrl:1
	v_fmac_f32_dpp v13, v79, v5 quad_perm:[1,1,3,3] row_mask:0xf bank_mask:0xf bound_ctrl:1
	ds_write2st64_b32 v30, v12, v13 offset0:14 offset1:15
	ds_read_b128 v[142:145], v34
	ds_read_b128 v[146:149], v34 offset:16
	ds_read_b128 v[150:153], v34 offset:32
	ds_read_b128 v[154:157], v34 offset:48
	v_add_u32_e32 v182, 16, v32
	v_cndmask_b32_e32 v182, v23, v182, vcc
	v_add_u32_e32 v182, s4, v182
	v_mad_i64_i32 v[180:181], s[6:7], v182, s10, v[24:25]
	s_waitcnt lgkmcnt(3)
	v_add_f32_e32 v158, v142, v143
	v_add_f32_e32 v159, v144, v145
	v_add_f32_e32 v158, v158, v159
	s_waitcnt lgkmcnt(2)
	v_add_f32_e32 v159, v146, v147
	v_add_f32_e32 v179, v148, v149
	v_add_f32_e32 v159, v159, v179
	v_add_f32_e32 v158, v158, v159
	s_waitcnt lgkmcnt(1)
	v_add_f32_e32 v159, v150, v151
	v_add_f32_e32 v179, v152, v153
	v_add_f32_e32 v159, v159, v179
	v_add_f32_e32 v158, v158, v159
	s_waitcnt lgkmcnt(0)
	v_add_f32_e32 v159, v154, v155
	v_add_f32_e32 v179, v156, v157
	v_add_f32_e32 v159, v159, v179
	v_add_f32_e32 v158, v158, v159
	global_store_dword v[180:181], v158, off
	v_add_u32_e32 v32, 32, v32
	v_subrev_u32_e32 v23, 32, v23
	s_waitcnt lgkmcnt(0)
	s_barrier
	s_cbranch_scc0 .LBB0_304
	s_setprio 0
